# ds_bpermute cross-lane reductions (xor 16 / xor 32) in the residual epilogue and the attention softmax replaced by v_permlane16/32_swap pairs (no LDS round trip); on top of the combined build
# speedup vs baseline: 1.0087x; 1.0016x over previous
; __device__ __forceinline__ unsigned cvt_pk_bf16(float lo, float hi) { const f32x2_e v = {lo, hi}; return __builtin_bit_cast(unsigned, __builtin_convertvector(v, bf16x2_e)); }
;     __device__ __forceinline__ void operator()(const f32x4 (&acc)[2][2][4][2], const Unit& u, int wr, int wc, int fr, int fq) const {
;     ...
;             for (int m = 0; m < 4; ++m) { const int row = row0 + ai * HALF + m * 16; const size_t off = (size_t)row * 1024 + col0; float ss = 0.f;
;                 f32x4 xf[2][2];
;                 if (base32) {
; #pragma unroll
;                     for (int bj = 0; bj < 2; ++bj) { xf[bj][0] = *(const f32x4*)(b32 + off + bj * HALF); xf[bj][1] = *(const f32x4*)(b32 + off + bj * HALF + 4); } }
; #pragma unroll
;                 for (int bj = 0; bj < 2; ++bj) {
;                     f32x4 x0, x1;
;                     if (base32) { x0 = xf[bj][0]; x1 = xf[bj][1]; }
;                     else { const u32x4 o = xo[m][bj]; x0 = (f32x4){bf_lo(o.x), bf_hi(o.x), bf_lo(o.y), bf_hi(o.y)}; x1 = (f32x4){bf_lo(o.z), bf_hi(o.z), bf_lo(o.w), bf_hi(o.w)}; }
;                     x0 += acc[ai][bj][m][0]; x1 += acc[ai][bj][m][1];
;                     if (out32) { *(f32x4*)(out32 + off + bj * HALF) = x0; *(f32x4*)(out32 + off + bj * HALF + 4) = x1; }
;                     ss += (x0[0] * x0[0] + x0[1] * x0[1]) + (x0[2] * x0[2] + x0[3] * x0[3]) + (x1[0] * x1[0] + x1[1] * x1[1]) + (x1[2] * x1[2] + x1[3] * x1[3]);
;                     u32x4 w; w.x = cvt_pk_bf16(x0[0], x0[1]); w.y = cvt_pk_bf16(x0[2], x0[3]); w.z = cvt_pk_bf16(x1[0], x1[1]); w.w = cvt_pk_bf16(x1[2], x1[3]);
;                     *(u32x4*)(XB + off + bj * HALF) = w; }
;                 ss += __shfl_xor(ss, 16); ss += __shfl_xor(ss, 32);
;                 if (fq == 0) SS[(size_t)row * 16 + 4 * u.pn + wc] = ss; }
.LBB0_117:
	v_mul_f32_e32 v64, v177, v177
	v_fmac_f32_e32 v64, v176, v176
	v_mul_f32_e32 v176, v179, v179
	v_fmac_f32_e32 v176, v178, v178
	v_mul_f32_e32 v173, v173, v173
	v_add_f32_e32 v64, v64, v176
	v_fmac_f32_e32 v173, v172, v172
	v_mul_f32_e32 v172, v175, v175
	v_add_f32_e32 v64, v64, v173
	v_fmac_f32_e32 v172, v174, v174
	v_and_b32_e32 v173, 64, v227
	v_pk_add_f32 v[170:171], v[170:171], v[214:215]
	v_pk_add_f32 v[168:169], v[168:169], v[212:213]
	v_add_f32_e32 v172, v172, v64
	v_xor_b32_e32 v64, 16, v227
	v_add_u32_e32 v173, 64, v173
	v_pk_add_f32 v[176:177], v[164:165], v[180:181]
	v_mul_f32_e32 v164, v169, v169
	v_mul_f32_e32 v165, v171, v171
	v_cmp_lt_i32_e32 vcc, v64, v173
	v_xor_b32_e32 v174, 32, v227
	v_fmac_f32_e32 v164, v168, v168
	v_fmac_f32_e32 v165, v170, v170
	v_cndmask_b32_e32 v64, v227, v64, vcc
	v_cmp_lt_i32_e32 vcc, v174, v173
	v_add_f32_e32 v164, v164, v165
	v_mul_f32_e32 v165, v177, v177
	v_cndmask_b32_e32 v173, v227, v174, vcc
	v_pk_add_f32 v[174:175], v[166:167], v[182:183]
	v_fmac_f32_e32 v165, v176, v176
	v_add_f32_e32 v164, v164, v165
	v_mul_f32_e32 v165, v175, v175
	v_fmac_f32_e32 v165, v174, v174
	v_add_f32_e32 v164, v165, v164
	v_lshlrev_b32_e32 v64, 2, v64
	v_add_f32_e32 v164, v172, v164
	v_mov_b32_e32 v165, v164
	s_nop 1
	v_permlane16_swap_b32_e32 v164, v165
	v_lshlrev_b32_e32 v172, 2, v173
	s_lshl_b32 s22, s50, 2
	s_ashr_i32 s23, s22, 31
	v_cvt_pk_bf16_f32 v166, v168, v169
	s_waitcnt lgkmcnt(0)
	v_add_f32_e32 v164, v164, v165
	v_mov_b32_e32 v165, v164
	s_nop 1
	v_permlane32_swap_b32_e32 v164, v165
	v_cvt_pk_bf16_f32 v167, v170, v171
	v_cvt_pk_bf16_f32 v168, v176, v177
	v_cvt_pk_bf16_f32 v169, v174, v175
	global_store_dwordx4 v[66:67], v[166:169], off offset:256
	s_and_saveexec_b64 s[20:21], s[42:43]
	s_cbranch_execz .LBB0_119
	v_readlane_b32 s50, v249, 7
	v_lshlrev_b64 v[66:67], 6, v[200:201]
	v_readlane_b32 s51, v249, 8
	s_lshl_b32 s90, s25, 2
	s_waitcnt lgkmcnt(0)
	v_add_f32_e32 v164, v164, v165
	v_lshl_add_u64 v[66:67], s[50:51], 0, v[66:67]
	v_lshl_add_u64 v[66:67], s[22:23], 2, v[66:67]
	v_lshl_add_u64 v[66:67], v[66:67], 0, s[90:91]
	global_store_dword v[66:67], v164, off

; __device__ __forceinline__ unsigned cvt_pk_bf16(float lo, float hi) { const f32x2_e v = {lo, hi}; return __builtin_bit_cast(unsigned, __builtin_convertvector(v, bf16x2_e)); }
;     __device__ __forceinline__ void operator()(const f32x4 (&acc)[2][2][4][2], const Unit& u, int wr, int wc, int fr, int fq) const {
;     ...
;             for (int m = 0; m < 4; ++m) { const int row = row0 + ai * HALF + m * 16; const size_t off = (size_t)row * 1024 + col0; float ss = 0.f;
;                 f32x4 xf[2][2];
;                 if (base32) {
; #pragma unroll
;                     for (int bj = 0; bj < 2; ++bj) { xf[bj][0] = *(const f32x4*)(b32 + off + bj * HALF); xf[bj][1] = *(const f32x4*)(b32 + off + bj * HALF + 4); } }
; #pragma unroll
;                 for (int bj = 0; bj < 2; ++bj) {
;                     f32x4 x0, x1;
;                     if (base32) { x0 = xf[bj][0]; x1 = xf[bj][1]; }
;                     else { const u32x4 o = xo[m][bj]; x0 = (f32x4){bf_lo(o.x), bf_hi(o.x), bf_lo(o.y), bf_hi(o.y)}; x1 = (f32x4){bf_lo(o.z), bf_hi(o.z), bf_lo(o.w), bf_hi(o.w)}; }
;                     x0 += acc[ai][bj][m][0]; x1 += acc[ai][bj][m][1];
;                     if (out32) { *(f32x4*)(out32 + off + bj * HALF) = x0; *(f32x4*)(out32 + off + bj * HALF + 4) = x1; }
;                     ss += (x0[0] * x0[0] + x0[1] * x0[1]) + (x0[2] * x0[2] + x0[3] * x0[3]) + (x1[0] * x1[0] + x1[1] * x1[1]) + (x1[2] * x1[2] + x1[3] * x1[3]);
;                     u32x4 w; w.x = cvt_pk_bf16(x0[0], x0[1]); w.y = cvt_pk_bf16(x0[2], x0[3]); w.z = cvt_pk_bf16(x1[0], x1[1]); w.w = cvt_pk_bf16(x1[2], x1[3]);
;                     *(u32x4*)(XB + off + bj * HALF) = w; }
;                 ss += __shfl_xor(ss, 16); ss += __shfl_xor(ss, 32);
;                 if (fq == 0) SS[(size_t)row * 16 + 4 * u.pn + wc] = ss; }
.LBB0_131:
	v_mul_f32_e32 v161, v161, v161
	v_fmac_f32_e32 v161, v160, v160
	v_mul_f32_e32 v160, v163, v163
	v_fmac_f32_e32 v160, v162, v162
	v_mul_f32_e32 v157, v157, v157
	v_add_f32_e32 v160, v161, v160
	v_fmac_f32_e32 v157, v156, v156
	v_add_f32_e32 v156, v160, v157
	v_mul_f32_e32 v157, v159, v159
	v_pk_add_f32 v[154:155], v[154:155], v[170:171]
	v_pk_add_f32 v[152:153], v[152:153], v[166:167]
	v_fmac_f32_e32 v157, v158, v158
	v_pk_add_f32 v[158:159], v[148:149], v[164:165]
	v_mul_f32_e32 v148, v153, v153
	v_mul_f32_e32 v149, v155, v155
	v_fmac_f32_e32 v148, v152, v152
	v_fmac_f32_e32 v149, v154, v154
	v_add_f32_e32 v148, v148, v149
	v_mul_f32_e32 v149, v159, v159
	v_add_f32_e32 v160, v157, v156
	v_pk_add_f32 v[156:157], v[150:151], v[168:169]
	v_fmac_f32_e32 v149, v158, v158
	v_add_f32_e32 v148, v148, v149
	v_mul_f32_e32 v149, v157, v157
	v_fmac_f32_e32 v149, v156, v156
	v_add_f32_e32 v148, v149, v148
	v_add_f32_e32 v148, v160, v148
	v_mov_b32_e32 v149, v148
	s_nop 1
	v_permlane16_swap_b32_e32 v148, v149
	v_cvt_pk_bf16_f32 v150, v152, v153
	v_cvt_pk_bf16_f32 v151, v154, v155
	v_cvt_pk_bf16_f32 v152, v158, v159
	v_cvt_pk_bf16_f32 v153, v156, v157
	s_waitcnt lgkmcnt(0)
	v_add_f32_e32 v148, v148, v149
	v_mov_b32_e32 v149, v148
	s_nop 1
	v_permlane32_swap_b32_e32 v148, v149
	global_store_dwordx4 v[66:67], v[150:153], off offset:256
	s_and_saveexec_b64 s[20:21], s[42:43]
	s_cbranch_execz .LBB0_133
	v_readlane_b32 s50, v249, 7
	v_lshlrev_b64 v[66:67], 6, v[210:211]
	v_readlane_b32 s51, v249, 8
	s_lshl_b32 s90, s25, 2
	s_waitcnt lgkmcnt(0)
	v_add_f32_e32 v148, v148, v149
	v_lshl_add_u64 v[66:67], s[50:51], 0, v[66:67]
	v_lshl_add_u64 v[66:67], s[22:23], 2, v[66:67]
	v_lshl_add_u64 v[66:67], v[66:67], 0, s[90:91]
	global_store_dword v[66:67], v148, off

; __device__ __forceinline__ unsigned cvt_pk_bf16(float lo, float hi) { const f32x2_e v = {lo, hi}; return __builtin_bit_cast(unsigned, __builtin_convertvector(v, bf16x2_e)); }
;     __device__ __forceinline__ void operator()(const f32x4 (&acc)[2][2][4][2], const Unit& u, int wr, int wc, int fr, int fq) const {
;     ...
;             for (int m = 0; m < 4; ++m) { const int row = row0 + ai * HALF + m * 16; const size_t off = (size_t)row * 1024 + col0; float ss = 0.f;
;                 f32x4 xf[2][2];
;                 if (base32) {
; #pragma unroll
;                     for (int bj = 0; bj < 2; ++bj) { xf[bj][0] = *(const f32x4*)(b32 + off + bj * HALF); xf[bj][1] = *(const f32x4*)(b32 + off + bj * HALF + 4); } }
; #pragma unroll
;                 for (int bj = 0; bj < 2; ++bj) {
;                     f32x4 x0, x1;
;                     if (base32) { x0 = xf[bj][0]; x1 = xf[bj][1]; }
;                     else { const u32x4 o = xo[m][bj]; x0 = (f32x4){bf_lo(o.x), bf_hi(o.x), bf_lo(o.y), bf_hi(o.y)}; x1 = (f32x4){bf_lo(o.z), bf_hi(o.z), bf_lo(o.w), bf_hi(o.w)}; }
;                     x0 += acc[ai][bj][m][0]; x1 += acc[ai][bj][m][1];
;                     if (out32) { *(f32x4*)(out32 + off + bj * HALF) = x0; *(f32x4*)(out32 + off + bj * HALF + 4) = x1; }
;                     ss += (x0[0] * x0[0] + x0[1] * x0[1]) + (x0[2] * x0[2] + x0[3] * x0[3]) + (x1[0] * x1[0] + x1[1] * x1[1]) + (x1[2] * x1[2] + x1[3] * x1[3]);
;                     u32x4 w; w.x = cvt_pk_bf16(x0[0], x0[1]); w.y = cvt_pk_bf16(x0[2], x0[3]); w.z = cvt_pk_bf16(x1[0], x1[1]); w.w = cvt_pk_bf16(x1[2], x1[3]);
;                     *(u32x4*)(XB + off + bj * HALF) = w; }
;                 ss += __shfl_xor(ss, 16); ss += __shfl_xor(ss, 32);
;                 if (fq == 0) SS[(size_t)row * 16 + 4 * u.pn + wc] = ss; }
.LBB0_145:
	v_mul_f32_e32 v137, v137, v137
	v_fmac_f32_e32 v137, v136, v136
	v_mul_f32_e32 v136, v139, v139
	v_fmac_f32_e32 v136, v138, v138
	v_mul_f32_e32 v133, v133, v133
	v_add_f32_e32 v136, v137, v136
	v_fmac_f32_e32 v133, v132, v132
	v_add_f32_e32 v132, v136, v133
	v_mul_f32_e32 v133, v135, v135
	v_pk_add_f32 v[130:131], v[130:131], v[154:155]
	v_pk_add_f32 v[128:129], v[128:129], v[150:151]
	v_fmac_f32_e32 v133, v134, v134
	v_pk_add_f32 v[134:135], v[124:125], v[148:149]
	v_mul_f32_e32 v124, v129, v129
	v_mul_f32_e32 v125, v131, v131
	v_fmac_f32_e32 v124, v128, v128
	v_fmac_f32_e32 v125, v130, v130
	v_add_f32_e32 v124, v124, v125
	v_mul_f32_e32 v125, v135, v135
	v_add_f32_e32 v136, v133, v132
	v_pk_add_f32 v[132:133], v[126:127], v[152:153]
	v_fmac_f32_e32 v125, v134, v134
	v_add_f32_e32 v124, v124, v125
	v_mul_f32_e32 v125, v133, v133
	v_fmac_f32_e32 v125, v132, v132
	v_add_f32_e32 v124, v125, v124
	v_add_f32_e32 v124, v136, v124
	v_mov_b32_e32 v125, v124
	s_nop 1
	v_permlane16_swap_b32_e32 v124, v125
	v_cvt_pk_bf16_f32 v126, v128, v129
	v_cvt_pk_bf16_f32 v127, v130, v131
	v_cvt_pk_bf16_f32 v128, v134, v135
	v_cvt_pk_bf16_f32 v129, v132, v133
	s_waitcnt lgkmcnt(0)
	v_add_f32_e32 v124, v124, v125
	v_mov_b32_e32 v125, v124
	s_nop 1
	v_permlane32_swap_b32_e32 v124, v125
	global_store_dwordx4 v[66:67], v[126:129], off offset:256
	s_and_saveexec_b64 s[20:21], s[42:43]
	s_cbranch_execz .LBB0_147
	v_readlane_b32 s50, v249, 7
	v_lshlrev_b64 v[66:67], 6, v[208:209]
	v_readlane_b32 s51, v249, 8
	s_lshl_b32 s90, s25, 2
	s_waitcnt lgkmcnt(0)
	v_add_f32_e32 v124, v124, v125
	v_lshl_add_u64 v[66:67], s[50:51], 0, v[66:67]
	v_lshl_add_u64 v[66:67], s[22:23], 2, v[66:67]
	v_lshl_add_u64 v[66:67], v[66:67], 0, s[90:91]
	global_store_dword v[66:67], v124, off

; __device__ __forceinline__ unsigned cvt_pk_bf16(float lo, float hi) { const f32x2_e v = {lo, hi}; return __builtin_bit_cast(unsigned, __builtin_convertvector(v, bf16x2_e)); }
;     __device__ __forceinline__ void operator()(const f32x4 (&acc)[2][2][4][2], const Unit& u, int wr, int wc, int fr, int fq) const {
;     ...
;             for (int m = 0; m < 4; ++m) { const int row = row0 + ai * HALF + m * 16; const size_t off = (size_t)row * 1024 + col0; float ss = 0.f;
;                 f32x4 xf[2][2];
;                 if (base32) {
; #pragma unroll
;                     for (int bj = 0; bj < 2; ++bj) { xf[bj][0] = *(const f32x4*)(b32 + off + bj * HALF); xf[bj][1] = *(const f32x4*)(b32 + off + bj * HALF + 4); } }
; #pragma unroll
;                 for (int bj = 0; bj < 2; ++bj) {
;                     f32x4 x0, x1;
;                     if (base32) { x0 = xf[bj][0]; x1 = xf[bj][1]; }
;                     else { const u32x4 o = xo[m][bj]; x0 = (f32x4){bf_lo(o.x), bf_hi(o.x), bf_lo(o.y), bf_hi(o.y)}; x1 = (f32x4){bf_lo(o.z), bf_hi(o.z), bf_lo(o.w), bf_hi(o.w)}; }
;                     x0 += acc[ai][bj][m][0]; x1 += acc[ai][bj][m][1];
;                     if (out32) { *(f32x4*)(out32 + off + bj * HALF) = x0; *(f32x4*)(out32 + off + bj * HALF + 4) = x1; }
;                     ss += (x0[0] * x0[0] + x0[1] * x0[1]) + (x0[2] * x0[2] + x0[3] * x0[3]) + (x1[0] * x1[0] + x1[1] * x1[1]) + (x1[2] * x1[2] + x1[3] * x1[3]);
;                     u32x4 w; w.x = cvt_pk_bf16(x0[0], x0[1]); w.y = cvt_pk_bf16(x0[2], x0[3]); w.z = cvt_pk_bf16(x1[0], x1[1]); w.w = cvt_pk_bf16(x1[2], x1[3]);
;                     *(u32x4*)(XB + off + bj * HALF) = w; }
;                 ss += __shfl_xor(ss, 16); ss += __shfl_xor(ss, 32);
;                 if (fq == 0) SS[(size_t)row * 16 + 4 * u.pn + wc] = ss; }
.LBB0_159:
	v_mul_f32_e32 v113, v113, v113
	v_fmac_f32_e32 v113, v112, v112
	v_mul_f32_e32 v112, v115, v115
	v_fmac_f32_e32 v112, v114, v114
	v_mul_f32_e32 v109, v109, v109
	v_add_f32_e32 v112, v113, v112
	v_fmac_f32_e32 v109, v108, v108
	v_add_f32_e32 v108, v112, v109
	v_mul_f32_e32 v109, v111, v111
	v_fmac_f32_e32 v109, v110, v110
	v_pk_add_f32 v[106:107], v[106:107], v[130:131]
	v_pk_add_f32 v[104:105], v[104:105], v[126:127]
	v_add_f32_e32 v110, v109, v108
	v_pk_add_f32 v[108:109], v[96:97], v[124:125]
	v_mul_f32_e32 v96, v105, v105
	v_mul_f32_e32 v97, v107, v107
	v_fmac_f32_e32 v96, v104, v104
	v_fmac_f32_e32 v97, v106, v106
	v_add_f32_e32 v96, v96, v97
	v_mul_f32_e32 v97, v109, v109
	v_pk_add_f32 v[98:99], v[98:99], v[128:129]
	v_fmac_f32_e32 v97, v108, v108
	v_add_f32_e32 v96, v96, v97
	v_mul_f32_e32 v97, v99, v99
	v_fmac_f32_e32 v97, v98, v98
	v_add_f32_e32 v96, v97, v96
	v_add_f32_e32 v96, v110, v96
	v_mov_b32_e32 v97, v96
	s_nop 1
	v_permlane16_swap_b32_e32 v96, v97
	v_cvt_pk_bf16_f32 v104, v104, v105
	v_cvt_pk_bf16_f32 v105, v106, v107
	v_cvt_pk_bf16_f32 v106, v108, v109
	v_cvt_pk_bf16_f32 v107, v98, v99
	s_waitcnt lgkmcnt(0)
	v_add_f32_e32 v96, v96, v97
	v_mov_b32_e32 v97, v96
	s_nop 1
	v_permlane32_swap_b32_e32 v96, v97
	global_store_dwordx4 v[66:67], v[104:107], off offset:256
	s_and_saveexec_b64 s[20:21], s[42:43]
	s_cbranch_execz .LBB0_161
	v_readlane_b32 s50, v249, 7
	v_lshlrev_b64 v[66:67], 6, v[206:207]
	v_readlane_b32 s51, v249, 8
	s_lshl_b32 s90, s25, 2
	s_waitcnt lgkmcnt(0)
	v_add_f32_e32 v96, v96, v97
	v_lshl_add_u64 v[66:67], s[50:51], 0, v[66:67]
	v_lshl_add_u64 v[66:67], s[22:23], 2, v[66:67]
	v_lshl_add_u64 v[66:67], v[66:67], 0, s[90:91]
	global_store_dword v[66:67], v96, off

; __device__ __forceinline__ unsigned cvt_pk_bf16(float lo, float hi) { const f32x2_e v = {lo, hi}; return __builtin_bit_cast(unsigned, __builtin_convertvector(v, bf16x2_e)); }
;     __device__ __forceinline__ void operator()(const f32x4 (&acc)[2][2][4][2], const Unit& u, int wr, int wc, int fr, int fq) const {
;     ...
;             for (int m = 0; m < 4; ++m) { const int row = row0 + ai * HALF + m * 16; const size_t off = (size_t)row * 1024 + col0; float ss = 0.f;
;                 f32x4 xf[2][2];
;                 if (base32) {
; #pragma unroll
;                     for (int bj = 0; bj < 2; ++bj) { xf[bj][0] = *(const f32x4*)(b32 + off + bj * HALF); xf[bj][1] = *(const f32x4*)(b32 + off + bj * HALF + 4); } }
; #pragma unroll
;                 for (int bj = 0; bj < 2; ++bj) {
;                     f32x4 x0, x1;
;                     if (base32) { x0 = xf[bj][0]; x1 = xf[bj][1]; }
;                     else { const u32x4 o = xo[m][bj]; x0 = (f32x4){bf_lo(o.x), bf_hi(o.x), bf_lo(o.y), bf_hi(o.y)}; x1 = (f32x4){bf_lo(o.z), bf_hi(o.z), bf_lo(o.w), bf_hi(o.w)}; }
;                     x0 += acc[ai][bj][m][0]; x1 += acc[ai][bj][m][1];
;                     if (out32) { *(f32x4*)(out32 + off + bj * HALF) = x0; *(f32x4*)(out32 + off + bj * HALF + 4) = x1; }
;                     ss += (x0[0] * x0[0] + x0[1] * x0[1]) + (x0[2] * x0[2] + x0[3] * x0[3]) + (x1[0] * x1[0] + x1[1] * x1[1]) + (x1[2] * x1[2] + x1[3] * x1[3]);
;                     u32x4 w; w.x = cvt_pk_bf16(x0[0], x0[1]); w.y = cvt_pk_bf16(x0[2], x0[3]); w.z = cvt_pk_bf16(x1[0], x1[1]); w.w = cvt_pk_bf16(x1[2], x1[3]);
;                     *(u32x4*)(XB + off + bj * HALF) = w; }
;                 ss += __shfl_xor(ss, 16); ss += __shfl_xor(ss, 32);
;                 if (fq == 0) SS[(size_t)row * 16 + 4 * u.pn + wc] = ss; }
.LBB0_177:
	v_mul_f32_e32 v69, v69, v69
	v_fmac_f32_e32 v69, v68, v68
	v_mul_f32_e32 v68, v71, v71
	v_fmac_f32_e32 v68, v70, v70
	v_add_f32_e32 v68, v69, v68
	v_mul_f32_e32 v69, v99, v99
	v_fmac_f32_e32 v69, v98, v98
	v_mul_f32_e32 v63, v63, v63
	v_add_f32_e32 v68, v68, v69
	v_fmac_f32_e32 v63, v62, v62
	v_pk_add_f32 v[54:55], v[54:55], v[108:109]
	v_pk_add_f32 v[52:53], v[52:53], v[104:105]
	v_add_f32_e32 v70, v63, v68
	v_pk_add_f32 v[68:69], v[48:49], v[96:97]
	v_mul_f32_e32 v48, v53, v53
	v_mul_f32_e32 v49, v55, v55
	v_fmac_f32_e32 v48, v52, v52
	v_fmac_f32_e32 v49, v54, v54
	v_add_f32_e32 v48, v48, v49
	v_mul_f32_e32 v49, v69, v69
	v_pk_add_f32 v[62:63], v[50:51], v[106:107]
	v_fmac_f32_e32 v49, v68, v68
	v_add_f32_e32 v48, v48, v49
	v_mul_f32_e32 v49, v63, v63
	v_fmac_f32_e32 v49, v62, v62
	v_add_f32_e32 v48, v49, v48
	v_add_f32_e32 v48, v70, v48
	v_mov_b32_e32 v49, v48
	s_nop 1
	v_permlane16_swap_b32_e32 v48, v49
	v_cvt_pk_bf16_f32 v50, v52, v53
	v_cvt_pk_bf16_f32 v51, v54, v55
	v_cvt_pk_bf16_f32 v52, v68, v69
	v_cvt_pk_bf16_f32 v53, v62, v63
	s_waitcnt lgkmcnt(0)
	v_add_f32_e32 v48, v48, v49
	v_mov_b32_e32 v49, v48
	s_nop 1
	v_permlane32_swap_b32_e32 v48, v49
	global_store_dwordx4 v[60:61], v[50:53], off offset:256
	s_and_saveexec_b64 s[20:21], s[42:43]
	s_cbranch_execz .LBB0_179
	v_readlane_b32 s50, v249, 7
	v_lshlrev_b64 v[50:51], 6, v[66:67]
	v_readlane_b32 s51, v249, 8
	s_lshl_b32 s90, s25, 2
	s_waitcnt lgkmcnt(0)
	v_add_f32_e32 v48, v48, v49
	v_lshl_add_u64 v[50:51], s[50:51], 0, v[50:51]
	v_lshl_add_u64 v[50:51], s[22:23], 2, v[50:51]
	v_lshl_add_u64 v[50:51], v[50:51], 0, s[90:91]
	global_store_dword v[50:51], v48, off

; __device__ __forceinline__ unsigned cvt_pk_bf16(float lo, float hi) { const f32x2_e v = {lo, hi}; return __builtin_bit_cast(unsigned, __builtin_convertvector(v, bf16x2_e)); }
;     __device__ __forceinline__ void operator()(const f32x4 (&acc)[2][2][4][2], const Unit& u, int wr, int wc, int fr, int fq) const {
;     ...
;             for (int m = 0; m < 4; ++m) { const int row = row0 + ai * HALF + m * 16; const size_t off = (size_t)row * 1024 + col0; float ss = 0.f;
;                 f32x4 xf[2][2];
;                 if (base32) {
; #pragma unroll
;                     for (int bj = 0; bj < 2; ++bj) { xf[bj][0] = *(const f32x4*)(b32 + off + bj * HALF); xf[bj][1] = *(const f32x4*)(b32 + off + bj * HALF + 4); } }
; #pragma unroll
;                 for (int bj = 0; bj < 2; ++bj) {
;                     f32x4 x0, x1;
;                     if (base32) { x0 = xf[bj][0]; x1 = xf[bj][1]; }
;                     else { const u32x4 o = xo[m][bj]; x0 = (f32x4){bf_lo(o.x), bf_hi(o.x), bf_lo(o.y), bf_hi(o.y)}; x1 = (f32x4){bf_lo(o.z), bf_hi(o.z), bf_lo(o.w), bf_hi(o.w)}; }
;                     x0 += acc[ai][bj][m][0]; x1 += acc[ai][bj][m][1];
;                     if (out32) { *(f32x4*)(out32 + off + bj * HALF) = x0; *(f32x4*)(out32 + off + bj * HALF + 4) = x1; }
;                     ss += (x0[0] * x0[0] + x0[1] * x0[1]) + (x0[2] * x0[2] + x0[3] * x0[3]) + (x1[0] * x1[0] + x1[1] * x1[1]) + (x1[2] * x1[2] + x1[3] * x1[3]);
;                     u32x4 w; w.x = cvt_pk_bf16(x0[0], x0[1]); w.y = cvt_pk_bf16(x0[2], x0[3]); w.z = cvt_pk_bf16(x1[0], x1[1]); w.w = cvt_pk_bf16(x1[2], x1[3]);
;                     *(u32x4*)(XB + off + bj * HALF) = w; }
;                 ss += __shfl_xor(ss, 16); ss += __shfl_xor(ss, 32);
;                 if (fq == 0) SS[(size_t)row * 16 + 4 * u.pn + wc] = ss; }
.LBB0_191:
	v_mul_f32_e32 v45, v45, v45
	v_fmac_f32_e32 v45, v44, v44
	v_mul_f32_e32 v44, v47, v47
	v_fmac_f32_e32 v44, v46, v46
	v_add_f32_e32 v44, v45, v44
	v_mul_f32_e32 v45, v53, v53
	v_fmac_f32_e32 v45, v52, v52
	v_mul_f32_e32 v43, v43, v43
	v_add_f32_e32 v44, v44, v45
	v_fmac_f32_e32 v43, v42, v42
	v_pk_add_f32 v[38:39], v[38:39], v[62:63]
	v_pk_add_f32 v[36:37], v[36:37], v[54:55]
	v_add_f32_e32 v46, v43, v44
	v_pk_add_f32 v[44:45], v[32:33], v[50:51]
	v_mul_f32_e32 v32, v37, v37
	v_mul_f32_e32 v33, v39, v39
	v_fmac_f32_e32 v32, v36, v36
	v_fmac_f32_e32 v33, v38, v38
	v_add_f32_e32 v32, v32, v33
	v_mul_f32_e32 v33, v45, v45
	v_pk_add_f32 v[42:43], v[34:35], v[60:61]
	v_fmac_f32_e32 v33, v44, v44
	v_add_f32_e32 v32, v32, v33
	v_mul_f32_e32 v33, v43, v43
	v_fmac_f32_e32 v33, v42, v42
	v_add_f32_e32 v32, v33, v32
	v_add_f32_e32 v32, v46, v32
	v_mov_b32_e32 v33, v32
	s_nop 1
	v_permlane16_swap_b32_e32 v32, v33
	v_cvt_pk_bf16_f32 v34, v36, v37
	v_cvt_pk_bf16_f32 v35, v38, v39
	v_cvt_pk_bf16_f32 v36, v44, v45
	v_cvt_pk_bf16_f32 v37, v42, v43
	s_waitcnt lgkmcnt(0)
	v_add_f32_e32 v32, v32, v33
	v_mov_b32_e32 v33, v32
	s_nop 1
	v_permlane32_swap_b32_e32 v32, v33
	global_store_dwordx4 v[40:41], v[34:37], off offset:256
	s_and_saveexec_b64 s[20:21], s[42:43]
	s_cbranch_execz .LBB0_193
	v_readlane_b32 s50, v249, 7
	v_lshlrev_b64 v[34:35], 6, v[48:49]
	v_readlane_b32 s51, v249, 8
	s_lshl_b32 s90, s25, 2
	s_waitcnt lgkmcnt(0)
	v_add_f32_e32 v32, v32, v33
	v_lshl_add_u64 v[34:35], s[50:51], 0, v[34:35]
	v_lshl_add_u64 v[34:35], s[22:23], 2, v[34:35]
	v_lshl_add_u64 v[34:35], v[34:35], 0, s[90:91]
	global_store_dword v[34:35], v32, off

; __device__ __forceinline__ unsigned cvt_pk_bf16(float lo, float hi) { const f32x2_e v = {lo, hi}; return __builtin_bit_cast(unsigned, __builtin_convertvector(v, bf16x2_e)); }
;     __device__ __forceinline__ void operator()(const f32x4 (&acc)[2][2][4][2], const Unit& u, int wr, int wc, int fr, int fq) const {
;     ...
;             for (int m = 0; m < 4; ++m) { const int row = row0 + ai * HALF + m * 16; const size_t off = (size_t)row * 1024 + col0; float ss = 0.f;
;                 f32x4 xf[2][2];
;                 if (base32) {
; #pragma unroll
;                     for (int bj = 0; bj < 2; ++bj) { xf[bj][0] = *(const f32x4*)(b32 + off + bj * HALF); xf[bj][1] = *(const f32x4*)(b32 + off + bj * HALF + 4); } }
; #pragma unroll
;                 for (int bj = 0; bj < 2; ++bj) {
;                     f32x4 x0, x1;
;                     if (base32) { x0 = xf[bj][0]; x1 = xf[bj][1]; }
;                     else { const u32x4 o = xo[m][bj]; x0 = (f32x4){bf_lo(o.x), bf_hi(o.x), bf_lo(o.y), bf_hi(o.y)}; x1 = (f32x4){bf_lo(o.z), bf_hi(o.z), bf_lo(o.w), bf_hi(o.w)}; }
;                     x0 += acc[ai][bj][m][0]; x1 += acc[ai][bj][m][1];
;                     if (out32) { *(f32x4*)(out32 + off + bj * HALF) = x0; *(f32x4*)(out32 + off + bj * HALF + 4) = x1; }
;                     ss += (x0[0] * x0[0] + x0[1] * x0[1]) + (x0[2] * x0[2] + x0[3] * x0[3]) + (x1[0] * x1[0] + x1[1] * x1[1]) + (x1[2] * x1[2] + x1[3] * x1[3]);
;                     u32x4 w; w.x = cvt_pk_bf16(x0[0], x0[1]); w.y = cvt_pk_bf16(x0[2], x0[3]); w.z = cvt_pk_bf16(x1[0], x1[1]); w.w = cvt_pk_bf16(x1[2], x1[3]);
;                     *(u32x4*)(XB + off + bj * HALF) = w; }
;                 ss += __shfl_xor(ss, 16); ss += __shfl_xor(ss, 32);
;                 if (fq == 0) SS[(size_t)row * 16 + 4 * u.pn + wc] = ss; }
.LBB0_205:
	v_mul_f32_e32 v29, v29, v29
	v_fmac_f32_e32 v29, v28, v28
	v_mul_f32_e32 v28, v31, v31
	v_fmac_f32_e32 v28, v30, v30
	v_add_f32_e32 v28, v29, v28
	v_mul_f32_e32 v29, v37, v37
	v_fmac_f32_e32 v29, v36, v36
	v_mul_f32_e32 v27, v27, v27
	v_add_f32_e32 v28, v28, v29
	v_fmac_f32_e32 v27, v26, v26
	v_pk_add_f32 v[22:23], v[22:23], v[42:43]
	v_pk_add_f32 v[20:21], v[20:21], v[38:39]
	v_add_f32_e32 v30, v27, v28
	v_pk_add_f32 v[28:29], v[16:17], v[34:35]
	v_mul_f32_e32 v16, v21, v21
	v_mul_f32_e32 v17, v23, v23
	v_fmac_f32_e32 v16, v20, v20
	v_fmac_f32_e32 v17, v22, v22
	v_add_f32_e32 v16, v16, v17
	v_mul_f32_e32 v17, v29, v29
	v_pk_add_f32 v[26:27], v[18:19], v[40:41]
	v_fmac_f32_e32 v17, v28, v28
	v_add_f32_e32 v16, v16, v17
	v_mul_f32_e32 v17, v27, v27
	v_fmac_f32_e32 v17, v26, v26
	v_add_f32_e32 v16, v17, v16
	v_add_f32_e32 v16, v30, v16
	v_mov_b32_e32 v17, v16
	s_nop 1
	v_permlane16_swap_b32_e32 v16, v17
	v_cvt_pk_bf16_f32 v18, v20, v21
	v_cvt_pk_bf16_f32 v19, v22, v23
	v_cvt_pk_bf16_f32 v20, v28, v29
	v_cvt_pk_bf16_f32 v21, v26, v27
	s_waitcnt lgkmcnt(0)
	v_add_f32_e32 v16, v16, v17
	v_mov_b32_e32 v17, v16
	s_nop 1
	v_permlane32_swap_b32_e32 v16, v17
	global_store_dwordx4 v[24:25], v[18:21], off offset:256
	s_and_saveexec_b64 s[20:21], s[42:43]
	s_cbranch_execz .LBB0_207
	v_readlane_b32 s50, v249, 7
	v_lshlrev_b64 v[18:19], 6, v[32:33]
	v_readlane_b32 s51, v249, 8
	s_lshl_b32 s90, s25, 2
	s_waitcnt lgkmcnt(0)
	v_add_f32_e32 v16, v16, v17
	v_lshl_add_u64 v[18:19], s[50:51], 0, v[18:19]
	v_lshl_add_u64 v[18:19], s[22:23], 2, v[18:19]
	v_lshl_add_u64 v[18:19], v[18:19], 0, s[90:91]
	global_store_dword v[18:19], v16, off

; __device__ __forceinline__ unsigned cvt_pk_bf16(float lo, float hi) { const f32x2_e v = {lo, hi}; return __builtin_bit_cast(unsigned, __builtin_convertvector(v, bf16x2_e)); }
;     __device__ __forceinline__ void operator()(const f32x4 (&acc)[2][2][4][2], const Unit& u, int wr, int wc, int fr, int fq) const {
;     ...
;             for (int m = 0; m < 4; ++m) { const int row = row0 + ai * HALF + m * 16; const size_t off = (size_t)row * 1024 + col0; float ss = 0.f;
;                 f32x4 xf[2][2];
;                 if (base32) {
; #pragma unroll
;                     for (int bj = 0; bj < 2; ++bj) { xf[bj][0] = *(const f32x4*)(b32 + off + bj * HALF); xf[bj][1] = *(const f32x4*)(b32 + off + bj * HALF + 4); } }
; #pragma unroll
;                 for (int bj = 0; bj < 2; ++bj) {
;                     f32x4 x0, x1;
;                     if (base32) { x0 = xf[bj][0]; x1 = xf[bj][1]; }
;                     else { const u32x4 o = xo[m][bj]; x0 = (f32x4){bf_lo(o.x), bf_hi(o.x), bf_lo(o.y), bf_hi(o.y)}; x1 = (f32x4){bf_lo(o.z), bf_hi(o.z), bf_lo(o.w), bf_hi(o.w)}; }
;                     x0 += acc[ai][bj][m][0]; x1 += acc[ai][bj][m][1];
;                     if (out32) { *(f32x4*)(out32 + off + bj * HALF) = x0; *(f32x4*)(out32 + off + bj * HALF + 4) = x1; }
;                     ss += (x0[0] * x0[0] + x0[1] * x0[1]) + (x0[2] * x0[2] + x0[3] * x0[3]) + (x1[0] * x1[0] + x1[1] * x1[1]) + (x1[2] * x1[2] + x1[3] * x1[3]);
;                     u32x4 w; w.x = cvt_pk_bf16(x0[0], x0[1]); w.y = cvt_pk_bf16(x0[2], x0[3]); w.z = cvt_pk_bf16(x1[0], x1[1]); w.w = cvt_pk_bf16(x1[2], x1[3]);
;                     *(u32x4*)(XB + off + bj * HALF) = w; }
;                 ss += __shfl_xor(ss, 16); ss += __shfl_xor(ss, 32);
;                 if (fq == 0) SS[(size_t)row * 16 + 4 * u.pn + wc] = ss; }
.LBB0_215:
	v_mul_f32_e32 v13, v13, v13
	v_fmac_f32_e32 v13, v12, v12
	v_mul_f32_e32 v12, v15, v15
	v_fmac_f32_e32 v12, v14, v14
	v_add_f32_e32 v12, v13, v12
	v_mul_f32_e32 v13, v21, v21
	v_fmac_f32_e32 v13, v20, v20
	v_mul_f32_e32 v11, v11, v11
	v_add_f32_e32 v12, v12, v13
	v_fmac_f32_e32 v11, v10, v10
	s_waitcnt vmcnt(1)
	v_pk_add_f32 v[6:7], v[6:7], v[86:87]
	v_pk_add_f32 v[4:5], v[4:5], v[84:85]
	v_add_f32_e32 v14, v11, v12
	v_pk_add_f32 v[12:13], v[0:1], v[80:81]
	v_mul_f32_e32 v0, v5, v5
	v_mul_f32_e32 v1, v7, v7
	v_fmac_f32_e32 v0, v4, v4
	v_fmac_f32_e32 v1, v6, v6
	v_add_f32_e32 v0, v0, v1
	v_mul_f32_e32 v1, v13, v13
	v_pk_add_f32 v[10:11], v[2:3], v[82:83]
	v_fmac_f32_e32 v1, v12, v12
	v_add_f32_e32 v0, v0, v1
	v_mul_f32_e32 v1, v11, v11
	v_fmac_f32_e32 v1, v10, v10
	v_add_f32_e32 v0, v1, v0
	v_add_f32_e32 v0, v14, v0
	v_mov_b32_e32 v1, v0
	s_nop 1
	v_permlane16_swap_b32_e32 v0, v1
	v_cvt_pk_bf16_f32 v2, v4, v5
	v_cvt_pk_bf16_f32 v3, v6, v7
	v_cvt_pk_bf16_f32 v4, v12, v13
	v_cvt_pk_bf16_f32 v5, v10, v11
	s_waitcnt lgkmcnt(0)
	v_add_f32_e32 v0, v0, v1
	v_mov_b32_e32 v1, v0
	s_nop 1
	v_permlane32_swap_b32_e32 v0, v1
	global_store_dwordx4 v[8:9], v[2:5], off offset:256
	s_and_saveexec_b64 s[18:19], s[42:43]
	s_cbranch_execz .LBB0_217
	v_readlane_b32 s20, v249, 7
	v_lshlrev_b64 v[2:3], 6, v[16:17]
	v_readlane_b32 s21, v249, 8
	s_lshl_b32 s90, s25, 2
	s_waitcnt lgkmcnt(0)
	v_add_f32_e32 v0, v0, v1
	v_lshl_add_u64 v[2:3], s[20:21], 0, v[2:3]
	v_lshl_add_u64 v[2:3], s[22:23], 2, v[2:3]
	v_lshl_add_u64 v[2:3], v[2:3], 0, s[90:91]
	global_store_dword v[2:3], v0, off

; __device__ __forceinline__ f32x4 mfma16(bf16x8 a, bf16x8 b, f32x4 c) { return __builtin_amdgcn_mfma_f32_16x16x32_bf16(a, b, c, 0, 0, 0); }
; __device__ __forceinline__ void na_fast(const bf16* PROJ, const float* rpb, bf16* MIX, int L, LAS unsigned char* lds) {
;     ...
;         const size_t qtok = seqbase + (size_t)r * 64 + qc;
;         bf16x8 qf[2];
; #pragma unroll
;         for (int ks = 0; ks < 2; ++ks) qf[ks] = *(const bf16x8*)(PROJ + qtok * EIN + 2560 + 64 * h + 32 * ks + 8 * g4);
;         f32x4 X[16];
;         {
;             const bf16* kbase = PROJ + (seqbase + (size_t)(rs0 * 64 + bs + r16)) * EIN + 3072 + 64 * h + 8 * g4;
;             bf16x8 k0[16], k1[16];
; #pragma unroll
;             for (int T = 0; T < 8; ++T) { const bf16* kp = kbase + (size_t)((T >> 1) * 64 + 16 * (T & 1)) * EIN; k0[2 * T] = *(const bf16x8*)kp; k0[2 * T + 1] = *(const bf16x8*)(kp + 32); }
; #pragma unroll
;             for (int T = 8; T < 16; ++T) { const bf16* kp = kbase + (size_t)((T >> 1) * 64 + 16 * (T & 1)) * EIN; k1[2 * (T - 8)] = *(const bf16x8*)kp; k1[2 * (T - 8) + 1] = *(const bf16x8*)(kp + 32); }
;             __builtin_amdgcn_sched_barrier(0);
; #pragma unroll
;             for (int T = 0; T < 8; ++T) { f32x4 acc = (f32x4){0.f, 0.f, 0.f, 0.f}; acc = mfma16(k0[2 * T], qf[0], acc); X[T] = mfma16(k0[2 * T + 1], qf[1], acc); }
; #pragma unroll
;             for (int T = 8; T < 16; ++T) { f32x4 acc = (f32x4){0.f, 0.f, 0.f, 0.f}; acc = mfma16(k1[2 * (T - 8)], qf[0], acc); X[T] = mfma16(k1[2 * (T - 8) + 1], qf[1], acc); }
.LBB0_453:
	v_lshl_add_u64 v[8:9], v[88:89], 0, s[6:7]
	v_add_co_u32_e32 v12, vcc, 0x6d01000, v8
	v_mov_b32_e32 v87, v65
	s_nop 0
	v_addc_co_u32_e32 v13, vcc, 0, v9, vcc
	global_load_dwordx4 v[8:11], v[12:13], off offset:1024
	global_load_dwordx4 v[122:125], v[12:13], off offset:1088
	v_lshl_add_u32 v12, s24, 6, v111
	v_ashrrev_i32_e32 v13, 31, v12
	v_lshl_add_u64 v[12:13], v[12:13], 0, s[90:91]
	v_lshlrev_b64 v[12:13], 13, v[12:13]
	v_lshl_add_u64 v[12:13], s[4:5], 0, v[12:13]
	v_lshl_add_u64 v[12:13], s[8:9], 1, v[12:13]
	v_lshl_add_u64 v[52:53], v[12:13], 0, v[86:87]
	v_add_co_u32_e32 v12, vcc, s93, v52
	s_mov_b32 s25, 0x21000
	s_nop 0
	v_addc_co_u32_e32 v13, vcc, 0, v53, vcc
	v_add_co_u32_e32 v24, vcc, s25, v52
	s_mov_b32 s25, 0x81000
	s_nop 0
	v_addc_co_u32_e32 v25, vcc, 0, v53, vcc
	v_add_co_u32_e32 v32, vcc, s25, v52
	s_mov_b32 s25, 0xa1000
	s_nop 0
	v_addc_co_u32_e32 v33, vcc, 0, v53, vcc
	v_add_co_u32_e32 v40, vcc, s25, v52
	s_mov_b32 s25, 0x101000
	s_nop 0
	v_addc_co_u32_e32 v41, vcc, 0, v53, vcc
	v_add_co_u32_e32 v48, vcc, s25, v52
	s_mov_b32 s25, 0x121000
	s_nop 0
	v_addc_co_u32_e32 v49, vcc, 0, v53, vcc
	s_mov_b64 s[26:27], 0x1800
	v_add_co_u32_e32 v54, vcc, s25, v52
	v_lshl_add_u64 v[16:17], v[52:53], 0, s[26:27]
	s_nop 0
	v_addc_co_u32_e32 v55, vcc, 0, v53, vcc
	s_mov_b32 s25, 0x181000
	global_load_dwordx4 v[12:15], v[12:13], off offset:2048
	s_nop 0
	global_load_dwordx4 v[16:19], v[16:17], off offset:64
	s_nop 0
	global_load_dwordx4 v[20:23], v[24:25], off offset:2048
	s_nop 0
	global_load_dwordx4 v[24:27], v[24:25], off offset:2112
	s_nop 0
	global_load_dwordx4 v[28:31], v[32:33], off offset:2048
	s_nop 0
	global_load_dwordx4 v[32:35], v[32:33], off offset:2112
	s_nop 0
	global_load_dwordx4 v[36:39], v[40:41], off offset:2048
	s_nop 0
	global_load_dwordx4 v[40:43], v[40:41], off offset:2112
	s_nop 0
	global_load_dwordx4 v[44:47], v[48:49], off offset:2048
	s_nop 0
	global_load_dwordx4 v[48:51], v[48:49], off offset:2112
	s_nop 0
	global_load_dwordx4 v[126:129], v[54:55], off offset:2048
	global_load_dwordx4 v[130:133], v[54:55], off offset:2112
	v_add_co_u32_e32 v54, vcc, s25, v52
	s_mov_b32 s25, 0x1a1000
	s_nop 0
	v_addc_co_u32_e32 v55, vcc, 0, v53, vcc
	global_load_dwordx4 v[134:137], v[54:55], off offset:2048
	global_load_dwordx4 v[138:141], v[54:55], off offset:2112
	v_add_co_u32_e32 v54, vcc, s25, v52
	s_mov_b32 s25, 0x201000
	s_nop 0
	v_addc_co_u32_e32 v55, vcc, 0, v53, vcc
	global_load_dwordx4 v[142:145], v[54:55], off offset:2048
	global_load_dwordx4 v[146:149], v[54:55], off offset:2112
	v_add_co_u32_e32 v54, vcc, s25, v52
	s_mov_b32 s25, 0x221000
	s_nop 0
	v_addc_co_u32_e32 v55, vcc, 0, v53, vcc
	global_load_dwordx4 v[150:153], v[54:55], off offset:2048
	global_load_dwordx4 v[154:157], v[54:55], off offset:2112
	v_add_co_u32_e32 v54, vcc, s25, v52
	s_mov_b32 s25, 0x281000
	s_nop 0
	v_addc_co_u32_e32 v55, vcc, 0, v53, vcc
	global_load_dwordx4 v[158:161], v[54:55], off offset:2048
	global_load_dwordx4 v[162:165], v[54:55], off offset:2112
	v_add_co_u32_e32 v54, vcc, s25, v52
	s_mov_b32 s25, 0x2a1000
	s_nop 0
	v_addc_co_u32_e32 v55, vcc, 0, v53, vcc
	global_load_dwordx4 v[166:169], v[54:55], off offset:2048
	global_load_dwordx4 v[170:173], v[54:55], off offset:2112
	v_add_co_u32_e32 v54, vcc, s25, v52
	s_mov_b32 s25, 0x301000
	s_nop 0
	v_addc_co_u32_e32 v55, vcc, 0, v53, vcc
	global_load_dwordx4 v[174:177], v[54:55], off offset:2048
	global_load_dwordx4 v[178:181], v[54:55], off offset:2112
	v_add_co_u32_e32 v54, vcc, s25, v52
	s_mov_b32 s25, 0x321000
	s_nop 0
	v_addc_co_u32_e32 v55, vcc, 0, v53, vcc
	global_load_dwordx4 v[188:191], v[54:55], off offset:2048
	global_load_dwordx4 v[192:195], v[54:55], off offset:2112
	v_add_co_u32_e32 v54, vcc, s25, v52
	s_mov_b32 s25, 0x381000
	s_nop 0
	v_addc_co_u32_e32 v55, vcc, 0, v53, vcc
	global_load_dwordx4 v[196:199], v[54:55], off offset:2048
	global_load_dwordx4 v[200:203], v[54:55], off offset:2112
	v_add_co_u32_e32 v54, vcc, s25, v52
	s_mov_b32 s25, 0x3a1000
	s_nop 0
	v_addc_co_u32_e32 v55, vcc, 0, v53, vcc
	v_add_co_u32_e32 v52, vcc, s25, v52
	global_load_dwordx4 v[204:207], v[54:55], off offset:2048
	global_load_dwordx4 v[208:211], v[54:55], off offset:2112
	v_addc_co_u32_e32 v53, vcc, 0, v53, vcc
	global_load_dwordx4 v[212:215], v[52:53], off offset:2048
	global_load_dwordx4 v[216:219], v[52:53], off offset:2112
	s_waitcnt vmcnt(31)
	v_mfma_f32_16x16x32_bf16 v[12:15], v[12:15], v[8:11], 0
	s_add_i32 s25, s24, s13
	s_mulk_i32 s25, 0x7c
	s_add_i32 s25, s20, s25
	s_waitcnt vmcnt(30)
	v_mfma_f32_16x16x32_bf16 v[70:73], v[16:19], v[122:125], v[12:15]
	v_lshl_add_u32 v92, v93, 2, s25
	v_add_u32_e32 v85, 0x200, v92
	v_lshl_add_u32 v121, v94, 2, s25
	s_waitcnt vmcnt(29)
	v_mfma_f32_16x16x32_bf16 v[12:15], v[20:23], v[8:11], 0
	s_mov_b32 s26, 0xf149f2ca
	s_lshl_b32 s24, s24, 13
	s_waitcnt vmcnt(28)
	v_mfma_f32_16x16x32_bf16 v[66:69], v[24:27], v[122:125], v[12:15]
	s_waitcnt vmcnt(27)
	v_mfma_f32_16x16x32_bf16 v[12:15], v[28:31], v[8:11], 0
	s_waitcnt vmcnt(26)
	v_mfma_f32_16x16x32_bf16 v[60:63], v[32:35], v[122:125], v[12:15]
	s_waitcnt vmcnt(25)
	v_mfma_f32_16x16x32_bf16 v[12:15], v[36:39], v[8:11], 0
	s_waitcnt vmcnt(24)
	v_mfma_f32_16x16x32_bf16 v[56:59], v[40:43], v[122:125], v[12:15]
	s_waitcnt vmcnt(23)
	v_mfma_f32_16x16x32_bf16 v[12:15], v[44:47], v[8:11], 0
	s_waitcnt vmcnt(22)
	v_mfma_f32_16x16x32_bf16 v[52:55], v[48:51], v[122:125], v[12:15]
	s_waitcnt vmcnt(21)
	v_mfma_f32_16x16x32_bf16 v[12:15], v[126:129], v[8:11], 0
	s_waitcnt vmcnt(20)
	v_mfma_f32_16x16x32_bf16 v[48:51], v[130:133], v[122:125], v[12:15]
	s_waitcnt vmcnt(19)
; #define LAS __attribute__((address_space(3)))
; __device__ __forceinline__ f32x4 mfma16(bf16x8 a, bf16x8 b, f32x4 c) { return __builtin_amdgcn_mfma_f32_16x16x32_bf16(a, b, c, 0, 0, 0); }
; __device__ __forceinline__ void na_fast(const bf16* PROJ, const float* rpb, bf16* MIX, int L, LAS unsigned char* lds) {
;     ...
;             for (int T = 0; T < 8; ++T) { f32x4 acc = (f32x4){0.f, 0.f, 0.f, 0.f}; acc = mfma16(k0[2 * T], qf[0], acc); X[T] = mfma16(k0[2 * T + 1], qf[1], acc); }
; #pragma unroll
;             for (int T = 8; T < 16; ++T) { f32x4 acc = (f32x4){0.f, 0.f, 0.f, 0.f}; acc = mfma16(k1[2 * (T - 8)], qf[0], acc); X[T] = mfma16(k1[2 * (T - 8) + 1], qf[1], acc); }
;         }
;         const LAS float* rp = RP + hh * 465 + (rs0 - r + 7) * 31;
;         float mx = -1e30f;
; #pragma unroll
;         for (int T = 0; T < 16; ++T) { const int kr = T >> 1, half = T & 1;
; #pragma unroll
;             for (int rr = 0; rr < 4; ++rr) { const int c8 = half * 4 + rr;
;                 const float sc = X[T][rr] * 0.125f + rp[kr * 31 + dcv[c8]];
;                 X[T][rr] = val[c8] ? sc : -1e30f; mx = fmaxf(mx, X[T][rr]); } }
	v_mfma_f32_16x16x32_bf16 v[12:15], v[134:137], v[8:11], 0
	s_waitcnt vmcnt(18)
	v_mfma_f32_16x16x32_bf16 v[44:47], v[138:141], v[122:125], v[12:15]
	v_lshl_add_u32 v138, v95, 2, s25
	v_add_u32_e32 v87, 0x200, v138
	v_lshl_add_u32 v139, v96, 2, s25
	s_waitcnt vmcnt(17)
	v_mfma_f32_16x16x32_bf16 v[12:15], v[142:145], v[8:11], 0
	ds_read2_b32 v[126:127], v87 offset0:104 offset1:135
	v_add_u32_e32 v87, 0x200, v139
	v_lshl_add_u32 v140, v97, 2, s25
	s_waitcnt vmcnt(16)
	v_mfma_f32_16x16x32_bf16 v[40:43], v[146:149], v[122:125], v[12:15]
	ds_read2_b32 v[128:129], v87 offset0:104 offset1:135
	v_add_u32_e32 v87, 0x200, v140
	v_lshl_add_u32 v141, v98, 2, s25
	s_waitcnt vmcnt(15)
	v_mfma_f32_16x16x32_bf16 v[12:15], v[150:153], v[8:11], 0
	ds_read2_b32 v[130:131], v87 offset0:104 offset1:135
	v_add_u32_e32 v87, 0x200, v141
	v_lshl_add_u32 v142, v99, 2, s25
	s_waitcnt vmcnt(14)
	v_mfma_f32_16x16x32_bf16 v[36:39], v[154:157], v[122:125], v[12:15]
	ds_read2_b32 v[132:133], v87 offset0:104 offset1:135
	v_add_u32_e32 v87, 0x200, v142
	v_lshl_add_u32 v143, v100, 2, s25
	s_waitcnt vmcnt(13)
	v_mfma_f32_16x16x32_bf16 v[12:15], v[158:161], v[8:11], 0
	ds_read2_b32 v[134:135], v87 offset0:104 offset1:135
	v_add_u32_e32 v87, 0x200, v143
	ds_read2_b32 v[136:137], v87 offset0:104 offset1:135
	s_waitcnt vmcnt(12)
	v_mfma_f32_16x16x32_bf16 v[32:35], v[162:165], v[122:125], v[12:15]
	s_waitcnt lgkmcnt(5)
	v_fmamk_f32 v72, v72, 0x3e000000, v126
	s_waitcnt lgkmcnt(4)
	v_fmamk_f32 v73, v73, 0x3e000000, v128
	v_cndmask_b32_e64 v72, v228, v72, s[46:47]
	s_waitcnt vmcnt(11)
	v_mfma_f32_16x16x32_bf16 v[12:15], v[166:169], v[8:11], 0
	v_cndmask_b32_e64 v73, v228, v73, s[48:49]
	s_waitcnt lgkmcnt(3)
	v_fmamk_f32 v66, v66, 0x3e000000, v130
	s_waitcnt lgkmcnt(2)
	v_fmamk_f32 v67, v67, 0x3e000000, v132
	s_waitcnt vmcnt(10)
	v_mfma_f32_16x16x32_bf16 v[28:31], v[170:173], v[122:125], v[12:15]
	v_cndmask_b32_e64 v66, v228, v66, s[50:51]
	v_cndmask_b32_e64 v67, v228, v67, s[52:53]
	s_waitcnt lgkmcnt(1)
	v_fmamk_f32 v68, v68, 0x3e000000, v134
	s_waitcnt vmcnt(9)
	v_mfma_f32_16x16x32_bf16 v[12:15], v[174:177], v[8:11], 0
	s_waitcnt lgkmcnt(0)
	v_fmamk_f32 v69, v69, 0x3e000000, v136
	v_cndmask_b32_e64 v68, v228, v68, s[54:55]
	v_cndmask_b32_e64 v87, v228, v69, s[56:57]
	s_waitcnt vmcnt(8)
	v_mfma_f32_16x16x32_bf16 v[24:27], v[178:181], v[122:125], v[12:15]
	v_add_u32_e32 v144, 0x400, v92
	v_add_u32_e32 v145, 0x400, v121
	v_fmac_f32_e32 v127, 0x3e000000, v62
	s_waitcnt vmcnt(7)
	v_mfma_f32_16x16x32_bf16 v[12:15], v[188:191], v[8:11], 0
	v_fmac_f32_e32 v129, 0x3e000000, v63
	v_add_u32_e32 v146, 0x400, v138
	v_add_u32_e32 v147, 0x400, v139
	s_waitcnt vmcnt(6)
	v_mfma_f32_16x16x32_bf16 v[20:23], v[192:195], v[122:125], v[12:15]
	v_cndmask_b32_e64 v62, v228, v127, s[46:47]
	v_fmac_f32_e32 v131, 0x3e000000, v56
	v_fmac_f32_e32 v133, 0x3e000000, v57
	s_waitcnt vmcnt(5)
	v_mfma_f32_16x16x32_bf16 v[12:15], v[196:199], v[8:11], 0
	ds_read2_b32 v[126:127], v146 offset0:38 offset1:69
	v_add_u32_e32 v140, 0x400, v140
	v_add_u32_e32 v141, 0x400, v141
	s_waitcnt vmcnt(4)
	v_mfma_f32_16x16x32_bf16 v[16:19], v[200:203], v[122:125], v[12:15]
	v_cndmask_b32_e64 v57, v228, v133, s[52:53]
	v_fmac_f32_e32 v135, 0x3e000000, v58
	v_fmac_f32_e32 v137, 0x3e000000, v59
	s_waitcnt vmcnt(3)
	v_mfma_f32_16x16x32_bf16 v[12:15], v[204:207], v[8:11], 0
	ds_read2_b32 v[132:133], v141 offset0:38 offset1:69
	v_add_u32_e32 v148, 0x400, v142
	v_add_u32_e32 v143, 0x400, v143
	s_waitcnt vmcnt(1)
	v_mfma_f32_16x16x32_bf16 v[8:11], v[212:215], v[8:11], 0
	v_cndmask_b32_e64 v58, v228, v135, s[54:55]
	v_cndmask_b32_e64 v56, v228, v137, s[56:57]
	ds_read2_b32 v[134:135], v148 offset0:38 offset1:69
	v_mfma_f32_16x16x32_bf16 v[12:15], v[208:211], v[122:125], v[12:15]
	ds_read2_b32 v[136:137], v143 offset0:38 offset1:69
	s_waitcnt lgkmcnt(3)
	v_fmamk_f32 v54, v54, 0x3e000000, v126
	v_cndmask_b32_e64 v54, v228, v54, s[46:47]
	s_waitcnt vmcnt(0)
	v_mfma_f32_16x16x32_bf16 v[8:11], v[216:219], v[122:125], v[8:11]
	ds_read2_b32 v[122:123], v85 offset0:104 offset1:135
	v_add_u32_e32 v85, 0x200, v121
	ds_read2_b32 v[124:125], v85 offset0:104 offset1:135
	s_waitcnt lgkmcnt(4)
	v_fmamk_f32 v49, v49, 0x3e000000, v132
	v_cndmask_b32_e64 v49, v228, v49, s[52:53]
	s_waitcnt lgkmcnt(1)
	v_fmamk_f32 v70, v70, 0x3e000000, v122
	v_cndmask_b32_e64 v70, v228, v70, s[42:43]
	s_waitcnt lgkmcnt(0)
	v_fmamk_f32 v71, v71, 0x3e000000, v124
	v_cndmask_b32_e64 v71, v228, v71, s[44:45]
	v_max3_f32 v85, v70, s26, v71
	v_max3_f32 v85, v85, v72, v73
	v_max3_f32 v85, v85, v66, v67
	v_fmac_f32_e32 v123, 0x3e000000, v60
	v_fmac_f32_e32 v125, 0x3e000000, v61
	v_max3_f32 v122, v85, v68, v87
	v_cndmask_b32_e64 v85, v228, v123, s[42:43]
	v_cndmask_b32_e64 v69, v228, v125, s[44:45]
	v_max3_f32 v60, v122, v85, v69
	ds_read2_b32 v[122:123], v144 offset0:38 offset1:69
	ds_read2_b32 v[124:125], v145 offset0:38 offset1:69
	v_cndmask_b32_e64 v61, v228, v129, s[48:49]
	ds_read2_b32 v[128:129], v147 offset0:38 offset1:69
	v_max3_f32 v63, v60, v62, v61
	v_cndmask_b32_e64 v60, v228, v131, s[50:51]
	ds_read2_b32 v[130:131], v140 offset0:38 offset1:69
	v_max3_f32 v63, v63, v60, v57
	s_waitcnt lgkmcnt(3)
	v_fmamk_f32 v52, v52, 0x3e000000, v122
	s_waitcnt lgkmcnt(2)
	v_fmamk_f32 v53, v53, 0x3e000000, v124
	v_max3_f32 v59, v63, v58, v56
	v_cndmask_b32_e64 v52, v228, v52, s[42:43]
	v_cndmask_b32_e64 v53, v228, v53, s[44:45]
	s_waitcnt lgkmcnt(1)
	v_fmamk_f32 v55, v55, 0x3e000000, v128
	v_max3_f32 v59, v59, v52, v53
	v_cndmask_b32_e64 v55, v228, v55, s[48:49]
	s_waitcnt lgkmcnt(0)
; #define LAS __attribute__((address_space(3)))
; __device__ __forceinline__ void na_fast(const bf16* PROJ, const float* rpb, bf16* MIX, int L, LAS unsigned char* lds) {
;     ...
;         const LAS float* rp = RP + hh * 465 + (rs0 - r + 7) * 31;
;         float mx = -1e30f;
; #pragma unroll
;         for (int T = 0; T < 16; ++T) { const int kr = T >> 1, half = T & 1;
; #pragma unroll
;             for (int rr = 0; rr < 4; ++rr) { const int c8 = half * 4 + rr;
;                 const float sc = X[T][rr] * 0.125f + rp[kr * 31 + dcv[c8]];
;                 X[T][rr] = val[c8] ? sc : -1e30f; mx = fmaxf(mx, X[T][rr]); } }
;         mx = fmaxf(mx, __shfl_xor(mx, 16)); mx = fmaxf(mx, __shfl_xor(mx, 32));
	v_fmamk_f32 v48, v48, 0x3e000000, v130
	v_max3_f32 v59, v59, v54, v55
	v_cndmask_b32_e64 v48, v228, v48, s[50:51]
	v_fmamk_f32 v50, v50, 0x3e000000, v134
	v_fmamk_f32 v51, v51, 0x3e000000, v136
	v_fmac_f32_e32 v123, 0x3e000000, v44
	v_max3_f32 v59, v59, v48, v49
	v_cndmask_b32_e64 v50, v228, v50, s[54:55]
	v_cndmask_b32_e64 v121, v228, v51, s[56:57]
	v_cndmask_b32_e64 v63, v228, v123, s[42:43]
	v_fmac_f32_e32 v125, 0x3e000000, v45
	v_fmac_f32_e32 v135, 0x3e000000, v42
	v_fmac_f32_e32 v137, 0x3e000000, v43
	ds_read2_b32 v[42:43], v144 offset0:100 offset1:131
	ds_read2_b32 v[122:123], v145 offset0:100 offset1:131
	v_max3_f32 v51, v59, v50, v121
	v_cndmask_b32_e64 v59, v228, v125, s[44:45]
	v_fmac_f32_e32 v127, 0x3e000000, v46
	ds_read2_b32 v[124:125], v146 offset0:100 offset1:131
	v_max3_f32 v44, v51, v63, v59
	v_cndmask_b32_e64 v51, v228, v127, s[46:47]
	v_fmac_f32_e32 v129, 0x3e000000, v47
	ds_read2_b32 v[126:127], v147 offset0:100 offset1:131
	v_cndmask_b32_e64 v46, v228, v129, s[48:49]
	v_fmac_f32_e32 v131, 0x3e000000, v40
	v_fmac_f32_e32 v133, 0x3e000000, v41
	v_max3_f32 v47, v44, v51, v46
	v_cndmask_b32_e64 v45, v228, v131, s[50:51]
	v_cndmask_b32_e64 v44, v228, v133, s[52:53]
	v_max3_f32 v47, v47, v45, v44
	v_cndmask_b32_e64 v41, v228, v135, s[54:55]
	v_cndmask_b32_e64 v40, v228, v137, s[56:57]
	s_waitcnt lgkmcnt(3)
	v_fmamk_f32 v36, v36, 0x3e000000, v42
	s_waitcnt lgkmcnt(2)
	v_fmamk_f32 v37, v37, 0x3e000000, v122
	v_max3_f32 v47, v47, v41, v40
	v_cndmask_b32_e64 v36, v228, v36, s[42:43]
	v_cndmask_b32_e64 v37, v228, v37, s[44:45]
	s_waitcnt lgkmcnt(1)
	v_fmamk_f32 v38, v38, 0x3e000000, v124
	v_max3_f32 v42, v47, v36, v37
	v_cndmask_b32_e64 v47, v228, v38, s[46:47]
	s_waitcnt lgkmcnt(0)
	v_fmamk_f32 v38, v39, 0x3e000000, v126
	v_cndmask_b32_e64 v92, v228, v38, s[48:49]
	ds_read2_b32 v[38:39], v140 offset0:100 offset1:131
	ds_read2_b32 v[132:133], v141 offset0:100 offset1:131
	ds_read2_b32 v[138:139], v143 offset0:100 offset1:131
	v_max3_f32 v42, v42, v47, v92
	v_fmac_f32_e32 v43, 0x3e000000, v28
	s_waitcnt lgkmcnt(2)
	v_fmamk_f32 v32, v32, 0x3e000000, v38
	v_cndmask_b32_e64 v122, v228, v32, s[50:51]
	s_waitcnt lgkmcnt(1)
	v_fmamk_f32 v32, v33, 0x3e000000, v132
	v_cndmask_b32_e64 v126, v228, v32, s[52:53]
	ds_read2_b32 v[32:33], v148 offset0:100 offset1:131
	v_max3_f32 v38, v42, v122, v126
	v_fmac_f32_e32 v123, 0x3e000000, v29
	v_cndmask_b32_e64 v135, v228, v43, s[42:43]
	v_cndmask_b32_e64 v134, v228, v123, s[44:45]
	s_waitcnt lgkmcnt(0)
	v_fmamk_f32 v32, v34, 0x3e000000, v32
	v_cndmask_b32_e64 v131, v228, v32, s[54:55]
	v_fmamk_f32 v32, v35, 0x3e000000, v138
	v_cndmask_b32_e64 v137, v228, v32, s[56:57]
	v_max3_f32 v32, v38, v131, v137
	v_fmac_f32_e32 v125, 0x3e000000, v30
	v_fmac_f32_e32 v127, 0x3e000000, v31
	v_max3_f32 v28, v32, v135, v134
	v_cndmask_b32_e64 v132, v228, v125, s[46:47]
	v_cndmask_b32_e64 v130, v228, v127, s[48:49]
	v_fmac_f32_e32 v39, 0x3e000000, v24
	v_fmac_f32_e32 v133, 0x3e000000, v25
	v_max3_f32 v28, v28, v132, v130
	v_cndmask_b32_e64 v129, v228, v39, s[50:51]
	v_cndmask_b32_e64 v127, v228, v133, s[52:53]
	v_fmac_f32_e32 v33, 0x3e000000, v26
	v_fmac_f32_e32 v139, 0x3e000000, v27
	v_max3_f32 v24, v28, v129, v127
	v_cndmask_b32_e64 v125, v228, v33, s[54:55]
	v_cndmask_b32_e64 v123, v228, v139, s[56:57]
	v_max3_f32 v28, v24, v125, v123
	ds_read2_b32 v[24:25], v144 offset0:162 offset1:193
	ds_read2_b32 v[26:27], v145 offset0:162 offset1:193
	ds_read2_b32 v[30:31], v141 offset0:162 offset1:193
	ds_read2_b32 v[32:33], v143 offset0:162 offset1:193
	s_and_b32 s25, s24, 0xe000
	s_waitcnt lgkmcnt(3)
	v_fmamk_f32 v20, v20, 0x3e000000, v24
	v_cndmask_b32_e64 v124, v228, v20, s[42:43]
	s_waitcnt lgkmcnt(2)
	v_fmamk_f32 v20, v21, 0x3e000000, v26
	v_cndmask_b32_e64 v128, v228, v20, s[44:45]
	ds_read2_b32 v[20:21], v146 offset0:162 offset1:193
	v_max3_f32 v24, v28, v124, v128
	ds_read2_b32 v[28:29], v147 offset0:162 offset1:193
	v_fmac_f32_e32 v25, 0x3e000000, v12
	v_fmac_f32_e32 v27, 0x3e000000, v13
	s_waitcnt lgkmcnt(1)
	v_fmamk_f32 v20, v22, 0x3e000000, v20
	v_cndmask_b32_e64 v133, v228, v20, s[46:47]
	s_waitcnt lgkmcnt(0)
	v_fmamk_f32 v20, v23, 0x3e000000, v28
	ds_read2_b32 v[22:23], v140 offset0:162 offset1:193
	v_cndmask_b32_e64 v136, v228, v20, s[48:49]
	v_max3_f32 v20, v24, v133, v136
	v_cndmask_b32_e64 v149, v228, v25, s[42:43]
	v_fmac_f32_e32 v21, 0x3e000000, v14
	s_waitcnt lgkmcnt(0)
	v_fmamk_f32 v16, v16, 0x3e000000, v22
	v_cndmask_b32_e64 v138, v228, v16, s[50:51]
	v_fmamk_f32 v16, v17, 0x3e000000, v30
	v_cndmask_b32_e64 v142, v228, v16, s[52:53]
	ds_read2_b32 v[16:17], v148 offset0:162 offset1:193
	v_max3_f32 v20, v20, v138, v142
	v_cndmask_b32_e64 v148, v228, v27, s[44:45]
	v_fmac_f32_e32 v29, 0x3e000000, v15
	v_cndmask_b32_e64 v147, v228, v21, s[46:47]
	s_waitcnt lgkmcnt(0)
	v_fmamk_f32 v16, v18, 0x3e000000, v16
	v_cndmask_b32_e64 v146, v228, v16, s[54:55]
	v_fmamk_f32 v16, v19, 0x3e000000, v32
	v_cndmask_b32_e64 v150, v228, v16, s[56:57]
	v_max3_f32 v16, v20, v146, v150
	v_max3_f32 v12, v16, v149, v148
	v_cndmask_b32_e64 v145, v228, v29, s[48:49]
	v_fmac_f32_e32 v23, 0x3e000000, v8
	v_fmac_f32_e32 v31, 0x3e000000, v9
	v_max3_f32 v12, v12, v147, v145
	v_cndmask_b32_e64 v144, v228, v23, s[50:51]
	v_cndmask_b32_e64 v143, v228, v31, s[52:53]
	v_fmac_f32_e32 v17, 0x3e000000, v10
	v_fmac_f32_e32 v33, 0x3e000000, v11
	v_max3_f32 v8, v12, v144, v143
	v_cndmask_b32_e64 v140, v228, v17, s[54:55]
	v_cndmask_b32_e64 v139, v228, v33, s[56:57]
	v_max3_f32 v8, v8, v140, v139
	v_mov_b32_e32 v9, v8
	s_nop 1
	v_permlane16_swap_b32_e32 v8, v9
	s_waitcnt lgkmcnt(0)
; __device__ __forceinline__ void na_fast(const bf16* PROJ, const float* rpb, bf16* MIX, int L, LAS unsigned char* lds) {
;     ...
;         mx = fmaxf(mx, __shfl_xor(mx, 16)); mx = fmaxf(mx, __shfl_xor(mx, 32));
;         float sum = 0.f;
; #pragma unroll
;         for (int T = 0; T < 16; ++T)
; #pragma unroll
;             for (int rr = 0; rr < 4; ++rr) { const float pw = __expf(X[T][rr] - mx); X[T][rr] = pw; sum += pw; }
	v_max_f32_e32 v9, v9, v9
	v_max_f32_e32 v8, v8, v9
	v_mov_b32_e32 v9, v8
	s_nop 1
	v_permlane32_swap_b32_e32 v8, v9
	s_waitcnt lgkmcnt(0)
	v_max_f32_e32 v9, v9, v9
	v_max_f32_e32 v141, v8, v9
	v_sub_f32_e32 v8, v70, v141
	v_mul_f32_e32 v8, 0x3fb8aa3b, v8
	v_sub_f32_e32 v9, v71, v141
	v_exp_f32_e32 v8, v8
	v_mul_f32_e32 v9, 0x3fb8aa3b, v9
	v_exp_f32_e32 v9, v9
	v_sub_f32_e32 v13, v66, v141
	v_add_f32_e32 v10, 0, v8
	v_mul_f32_e32 v13, 0x3fb8aa3b, v13
	v_add_f32_e32 v11, v9, v10
	v_sub_f32_e32 v10, v72, v141
	v_mul_f32_e32 v10, 0x3fb8aa3b, v10
	v_exp_f32_e32 v10, v10
	v_exp_f32_e32 v14, v13
	v_sub_f32_e32 v13, v67, v141
	v_mul_f32_e32 v13, 0x3fb8aa3b, v13
	v_add_f32_e32 v12, v10, v11
	v_sub_f32_e32 v11, v73, v141
	v_mul_f32_e32 v11, 0x3fb8aa3b, v11
	v_exp_f32_e32 v11, v11
	v_exp_f32_e32 v15, v13
	v_sub_f32_e32 v13, v68, v141
	v_mul_f32_e32 v13, 0x3fb8aa3b, v13
	v_exp_f32_e32 v18, v13
	v_sub_f32_e32 v13, v87, v141
	v_mul_f32_e32 v13, 0x3fb8aa3b, v13
	v_add_f32_e32 v12, v11, v12
	v_exp_f32_e32 v19, v13
	v_add_f32_e32 v12, v14, v12
	v_add_f32_e32 v12, v15, v12
	v_add_f32_e32 v12, v18, v12
	v_add_f32_e32 v13, v19, v12
	v_sub_f32_e32 v12, v85, v141
	v_mul_f32_e32 v12, 0x3fb8aa3b, v12
	v_exp_f32_e32 v12, v12
	v_sub_f32_e32 v21, v60, v141
	v_mul_f32_e32 v21, 0x3fb8aa3b, v21
	v_exp_f32_e32 v22, v21
	v_add_f32_e32 v16, v12, v13
	v_sub_f32_e32 v13, v69, v141
	v_mul_f32_e32 v13, 0x3fb8aa3b, v13
	v_exp_f32_e32 v13, v13
	v_sub_f32_e32 v21, v57, v141
	v_mul_f32_e32 v21, 0x3fb8aa3b, v21
	v_exp_f32_e32 v23, v21
	v_add_f32_e32 v17, v13, v16
	v_sub_f32_e32 v16, v62, v141
	v_mul_f32_e32 v16, 0x3fb8aa3b, v16
	v_exp_f32_e32 v16, v16
	v_sub_f32_e32 v21, v58, v141
	v_mul_f32_e32 v21, 0x3fb8aa3b, v21
	v_exp_f32_e32 v26, v21
	v_add_f32_e32 v20, v16, v17
	v_sub_f32_e32 v17, v61, v141
	v_mul_f32_e32 v17, 0x3fb8aa3b, v17
	v_exp_f32_e32 v17, v17
	v_sub_f32_e32 v21, v56, v141
	v_mul_f32_e32 v21, 0x3fb8aa3b, v21
	v_exp_f32_e32 v27, v21
	v_add_f32_e32 v20, v17, v20
	v_add_f32_e32 v20, v22, v20
	v_add_f32_e32 v20, v23, v20
	v_add_f32_e32 v20, v26, v20
	v_add_f32_e32 v21, v27, v20
	v_sub_f32_e32 v20, v52, v141
	v_mul_f32_e32 v20, 0x3fb8aa3b, v20
	v_exp_f32_e32 v20, v20
	v_sub_f32_e32 v29, v48, v141
	v_mul_f32_e32 v29, 0x3fb8aa3b, v29
	v_exp_f32_e32 v30, v29
	v_add_f32_e32 v24, v20, v21
	v_sub_f32_e32 v21, v53, v141
	v_mul_f32_e32 v21, 0x3fb8aa3b, v21
	v_exp_f32_e32 v21, v21
	v_sub_f32_e32 v29, v49, v141
	v_mul_f32_e32 v29, 0x3fb8aa3b, v29
	v_exp_f32_e32 v31, v29
	v_add_f32_e32 v25, v21, v24
	v_sub_f32_e32 v24, v54, v141
	v_mul_f32_e32 v24, 0x3fb8aa3b, v24
	v_exp_f32_e32 v24, v24
	v_sub_f32_e32 v29, v50, v141
	v_mul_f32_e32 v29, 0x3fb8aa3b, v29
	v_exp_f32_e32 v34, v29
	v_add_f32_e32 v28, v24, v25
	v_sub_f32_e32 v25, v55, v141
	v_mul_f32_e32 v25, 0x3fb8aa3b, v25
	v_exp_f32_e32 v25, v25
	v_sub_f32_e32 v29, v121, v141
	v_mul_f32_e32 v29, 0x3fb8aa3b, v29
	v_exp_f32_e32 v35, v29
	v_add_f32_e32 v28, v25, v28
	v_add_f32_e32 v28, v30, v28
	v_add_f32_e32 v28, v31, v28
	v_add_f32_e32 v28, v34, v28
	v_add_f32_e32 v29, v35, v28
	v_sub_f32_e32 v28, v63, v141
	v_mul_f32_e32 v28, 0x3fb8aa3b, v28
	v_exp_f32_e32 v28, v28
	v_sub_f32_e32 v41, v41, v141
	v_mul_f32_e32 v41, 0x3fb8aa3b, v41
	v_sub_f32_e32 v40, v40, v141
	v_add_f32_e32 v32, v28, v29
	v_sub_f32_e32 v29, v59, v141
	v_mul_f32_e32 v29, 0x3fb8aa3b, v29
	v_exp_f32_e32 v29, v29
	v_mul_f32_e32 v40, 0x3fb8aa3b, v40
	v_sub_f32_e32 v36, v36, v141
	v_mul_f32_e32 v36, 0x3fb8aa3b, v36
	v_add_f32_e32 v33, v29, v32
	v_sub_f32_e32 v32, v51, v141
	v_mul_f32_e32 v32, 0x3fb8aa3b, v32
	v_exp_f32_e32 v32, v32
	v_sub_f32_e32 v37, v37, v141
	v_exp_f32_e32 v36, v36
	v_mul_f32_e32 v37, 0x3fb8aa3b, v37
	v_add_f32_e32 v38, v32, v33
	v_sub_f32_e32 v33, v46, v141
	v_mul_f32_e32 v33, 0x3fb8aa3b, v33
	v_exp_f32_e32 v33, v33
	v_exp_f32_e32 v37, v37
	v_sub_f32_e32 v53, v129, v141
	v_mul_f32_e32 v53, 0x3fb8aa3b, v53
	v_add_f32_e32 v39, v33, v38
	v_sub_f32_e32 v38, v45, v141
	v_mul_f32_e32 v38, 0x3fb8aa3b, v38
	v_exp_f32_e32 v38, v38
	v_sub_f32_e32 v45, v122, v141
	v_mul_f32_e32 v45, 0x3fb8aa3b, v45
	v_exp_f32_e32 v46, v45
	v_add_f32_e32 v42, v38, v39
	v_sub_f32_e32 v39, v44, v141
	v_mul_f32_e32 v39, 0x3fb8aa3b, v39
	v_exp_f32_e32 v39, v39
	v_sub_f32_e32 v45, v126, v141
	v_mul_f32_e32 v45, 0x3fb8aa3b, v45
	v_exp_f32_e32 v54, v53
	v_add_f32_e32 v43, v39, v42
	v_exp_f32_e32 v42, v41
	v_sub_f32_e32 v53, v127, v141
	v_mul_f32_e32 v53, 0x3fb8aa3b, v53
	v_exp_f32_e32 v55, v53
	v_add_f32_e32 v41, v42, v43
	v_exp_f32_e32 v43, v40
	v_sub_f32_e32 v53, v125, v141
	v_mul_f32_e32 v53, 0x3fb8aa3b, v53
	v_exp_f32_e32 v58, v53
	v_add_f32_e32 v40, v43, v41
	v_add_f32_e32 v40, v36, v40
	v_add_f32_e32 v41, v37, v40
	v_sub_f32_e32 v40, v47, v141
	v_mul_f32_e32 v40, 0x3fb8aa3b, v40
	v_exp_f32_e32 v40, v40
	v_exp_f32_e32 v47, v45
	v_sub_f32_e32 v45, v131, v141
	v_mul_f32_e32 v45, 0x3fb8aa3b, v45
	v_add_f32_e32 v44, v40, v41
	v_sub_f32_e32 v41, v92, v141
	v_mul_f32_e32 v41, 0x3fb8aa3b, v41
	v_exp_f32_e32 v41, v41
	v_exp_f32_e32 v50, v45
	v_sub_f32_e32 v45, v137, v141
	v_mul_f32_e32 v45, 0x3fb8aa3b, v45
	v_add_f32_e32 v44, v41, v44
	v_exp_f32_e32 v51, v45
	v_add_f32_e32 v44, v46, v44
	v_add_f32_e32 v44, v47, v44
	v_add_f32_e32 v44, v50, v44
	v_add_f32_e32 v45, v51, v44
	v_sub_f32_e32 v44, v135, v141
	v_mul_f32_e32 v44, 0x3fb8aa3b, v44
	v_exp_f32_e32 v44, v44
	v_sub_f32_e32 v53, v123, v141
	v_mul_f32_e32 v53, 0x3fb8aa3b, v53
	v_exp_f32_e32 v59, v53
	v_add_f32_e32 v48, v44, v45
	v_sub_f32_e32 v45, v134, v141
	v_mul_f32_e32 v45, 0x3fb8aa3b, v45
	v_exp_f32_e32 v45, v45
	v_sub_f32_e32 v61, v138, v141
	v_mul_f32_e32 v61, 0x3fb8aa3b, v61
	v_exp_f32_e32 v62, v61
	v_add_f32_e32 v49, v45, v48
; __device__ __forceinline__ unsigned pk2(float lo, float hi) { const f32x2_t v = {lo, hi}; return __builtin_bit_cast(unsigned, __builtin_convertvector(v, bf16x2_t)); }
; __device__ __forceinline__ f32x4 mfma16(bf16x8 a, bf16x8 b, f32x4 c) { return __builtin_amdgcn_mfma_f32_16x16x32_bf16(a, b, c, 0, 0, 0); }
; template <int KP> __device__ __forceinline__ void na_pv_step(const f32x4 (&X)[16], float inv, const unsigned (&ad)[8], int rs0, f32x4 (&O)[4]) {
;     v4u aw; aw.x = pk2(X[2 * KP][0] * inv, X[2 * KP][1] * inv); aw.y = pk2(X[2 * KP][2] * inv, X[2 * KP][3] * inv);
;     aw.z = pk2(X[2 * KP + 1][0] * inv, X[2 * KP + 1][1] * inv); aw.w = pk2(X[2 * KP + 1][2] * inv, X[2 * KP + 1][3] * inv);
;     const unsigned soff = (unsigned)((rs0 + KP) & 7) * 8192u;
;     unsigned b[8]; s16x4 vr[8];
; #pragma unroll
;     for (int x = 0; x < 8; ++x) b[x] = ad[x] + soff;
;     tr_read8<0>(b, vr);
;     const bf16x8 af = as_bf8(aw);
; #pragma unroll
;     for (int dt = 0; dt < 4; ++dt) { const bf16x8 bw = (bf16x8){vr[2 * dt][0], vr[2 * dt][1], vr[2 * dt][2], vr[2 * dt][3], vr[2 * dt + 1][0], vr[2 * dt + 1][1], vr[2 * dt + 1][2], vr[2 * dt + 1][3]};
;         O[dt] = mfma16(af, bw, O[dt]); }
; }
; __device__ __forceinline__ void na_fast(const bf16* PROJ, const float* rpb, bf16* MIX, int L, LAS unsigned char* lds) {
;     ...
;             for (int rr = 0; rr < 4; ++rr) { const float pw = __expf(X[T][rr] - mx); X[T][rr] = pw; sum += pw; }
;         sum += __shfl_xor(sum, 16); sum += __shfl_xor(sum, 32);
;         const float inv = 1.0f / sum;
;         f32x4 O[4];
; #pragma unroll
;         for (int dt = 0; dt < 4; ++dt) O[dt] = (f32x4){0.f, 0.f, 0.f, 0.f};
;         na_pv_step<0>(X, inv, ad, rs0, O); na_pv_step<1>(X, inv, ad, rs0, O); na_pv_step<2>(X, inv, ad, rs0, O); na_pv_step<3>(X, inv, ad, rs0, O);
	v_sub_f32_e32 v48, v132, v141
	v_mul_f32_e32 v48, 0x3fb8aa3b, v48
	v_exp_f32_e32 v48, v48
	v_sub_f32_e32 v61, v142, v141
	v_mul_f32_e32 v61, 0x3fb8aa3b, v61
	v_exp_f32_e32 v63, v61
	v_add_f32_e32 v52, v48, v49
	v_sub_f32_e32 v49, v130, v141
	v_mul_f32_e32 v49, 0x3fb8aa3b, v49
	v_exp_f32_e32 v49, v49
	v_sub_f32_e32 v61, v146, v141
	v_mul_f32_e32 v61, 0x3fb8aa3b, v61
	v_exp_f32_e32 v68, v61
	v_add_f32_e32 v52, v49, v52
	v_add_f32_e32 v52, v54, v52
	v_add_f32_e32 v52, v55, v52
	v_add_f32_e32 v52, v58, v52
	v_add_f32_e32 v53, v59, v52
	v_sub_f32_e32 v52, v124, v141
	v_mul_f32_e32 v52, 0x3fb8aa3b, v52
	v_exp_f32_e32 v52, v52
	v_sub_f32_e32 v61, v150, v141
	v_mul_f32_e32 v61, 0x3fb8aa3b, v61
	v_exp_f32_e32 v69, v61
	v_add_f32_e32 v56, v52, v53
	v_sub_f32_e32 v53, v128, v141
	v_mul_f32_e32 v53, 0x3fb8aa3b, v53
	v_exp_f32_e32 v53, v53
	v_add_u32_e32 v138, s25, v108
	v_add_f32_e32 v57, v53, v56
	v_sub_f32_e32 v56, v133, v141
	v_mul_f32_e32 v56, 0x3fb8aa3b, v56
	v_exp_f32_e32 v56, v56
	s_nop 0
	v_add_f32_e32 v60, v56, v57
	v_sub_f32_e32 v57, v136, v141
	v_mul_f32_e32 v57, 0x3fb8aa3b, v57
	v_exp_f32_e32 v57, v57
	s_nop 0
	v_add_f32_e32 v60, v57, v60
	v_add_f32_e32 v60, v62, v60
	v_add_f32_e32 v60, v63, v60
	v_add_f32_e32 v60, v68, v60
	v_add_f32_e32 v61, v69, v60
	v_sub_f32_e32 v60, v149, v141
	v_mul_f32_e32 v60, 0x3fb8aa3b, v60
	v_exp_f32_e32 v60, v60
	s_nop 0
	v_add_f32_e32 v66, v60, v61
	v_sub_f32_e32 v61, v148, v141
	v_mul_f32_e32 v61, 0x3fb8aa3b, v61
	v_exp_f32_e32 v61, v61
	s_nop 0
	v_add_f32_e32 v67, v61, v66
	v_sub_f32_e32 v66, v147, v141
	v_mul_f32_e32 v66, 0x3fb8aa3b, v66
	v_exp_f32_e32 v66, v66
	s_nop 0
	v_add_f32_e32 v70, v66, v67
	v_sub_f32_e32 v67, v145, v141
	v_mul_f32_e32 v67, 0x3fb8aa3b, v67
	v_exp_f32_e32 v67, v67
	s_nop 0
	v_add_f32_e32 v71, v67, v70
	v_sub_f32_e32 v70, v144, v141
	v_mul_f32_e32 v70, 0x3fb8aa3b, v70
	v_exp_f32_e32 v70, v70
	s_nop 0
	v_add_f32_e32 v72, v70, v71
	v_sub_f32_e32 v71, v143, v141
	v_mul_f32_e32 v71, 0x3fb8aa3b, v71
	v_exp_f32_e32 v71, v71
	s_nop 0
	v_add_f32_e32 v73, v71, v72
	v_sub_f32_e32 v72, v140, v141
	v_mul_f32_e32 v72, 0x3fb8aa3b, v72
	v_exp_f32_e32 v72, v72
	s_nop 0
	v_add_f32_e32 v85, v72, v73
	v_sub_f32_e32 v73, v139, v141
	v_mul_f32_e32 v73, 0x3fb8aa3b, v73
	v_exp_f32_e32 v73, v73
	s_nop 0
	v_add_f32_e32 v85, v73, v85
	v_mov_b32_e32 v87, v85
	s_nop 1
	v_permlane16_swap_b32_e32 v85, v87
	s_waitcnt lgkmcnt(0)
	v_add_f32_e32 v85, v85, v87
	v_mov_b32_e32 v87, v85
	s_nop 1
	v_permlane32_swap_b32_e32 v85, v87
	s_waitcnt lgkmcnt(0)
	v_add_f32_e32 v85, v85, v87
	v_div_scale_f32 v87, s[26:27], v85, v85, 1.0
	v_rcp_f32_e32 v92, v87
	s_add_i32 s26, s24, 0x2000
	s_and_b32 s26, s26, 0xe000
	v_add_u32_e32 v146, s26, v108
	v_fma_f32 v121, -v87, v92, 1.0
	v_fmac_f32_e32 v92, v121, v92
	v_div_scale_f32 v121, vcc, 1.0, v85, 1.0
	v_mul_f32_e32 v122, v121, v92
	v_fma_f32 v123, -v87, v122, v121
	v_fmac_f32_e32 v122, v123, v92
	v_fma_f32 v87, -v87, v122, v121
	v_div_fmas_f32 v87, v87, v92, v122
	v_div_fixup_f32 v92, v87, v85, 1.0
	v_pk_mul_f32 v[8:9], v[8:9], v[92:93] op_sel_hi:[1,0]
	v_pk_mul_f32 v[10:11], v[10:11], v[92:93] op_sel_hi:[1,0]
	v_cvt_pk_bf16_f32 v8, v8, v9
	v_cvt_pk_bf16_f32 v9, v10, v11
	v_pk_mul_f32 v[10:11], v[14:15], v[92:93] op_sel_hi:[1,0]
	v_pk_mul_f32 v[14:15], v[18:19], v[92:93] op_sel_hi:[1,0]
	v_cvt_pk_bf16_f32 v10, v10, v11
	v_cvt_pk_bf16_f32 v11, v14, v15
	v_add_u32_e32 v14, s25, v101
	v_add_u32_e32 v15, s25, v102
	v_add_u32_e32 v18, s25, v103
	v_add_u32_e32 v19, s25, v104
	v_add_u32_e32 v85, s25, v105
	v_add_u32_e32 v87, s25, v106
	v_add_u32_e32 v121, s25, v107
	ds_read_b64_tr_b16 v[134:135], v14 offset:0
	ds_read_b64_tr_b16 v[136:137], v15 offset:0
	ds_read_b64_tr_b16 v[130:131], v18 offset:0
	ds_read_b64_tr_b16 v[132:133], v19 offset:0
	ds_read_b64_tr_b16 v[126:127], v85 offset:0
	ds_read_b64_tr_b16 v[128:129], v87 offset:0
	ds_read_b64_tr_b16 v[122:123], v121 offset:0
	ds_read_b64_tr_b16 v[124:125], v138 offset:0
	s_waitcnt lgkmcnt(0)
	v_pk_mul_f32 v[12:13], v[12:13], v[92:93] op_sel_hi:[1,0]
	v_pk_mul_f32 v[14:15], v[16:17], v[92:93] op_sel_hi:[1,0]
	v_cvt_pk_bf16_f32 v12, v12, v13
	v_cvt_pk_bf16_f32 v13, v14, v15
	v_pk_mul_f32 v[14:15], v[22:23], v[92:93] op_sel_hi:[1,0]
	v_pk_mul_f32 v[16:17], v[26:27], v[92:93] op_sel_hi:[1,0]
	v_cvt_pk_bf16_f32 v14, v14, v15
	v_cvt_pk_bf16_f32 v15, v16, v17
	v_mfma_f32_16x16x32_bf16 v[134:137], v[8:11], v[134:137], 0
	v_add_u32_e32 v22, s26, v101
	v_add_u32_e32 v23, s26, v102
	v_add_u32_e32 v26, s26, v103
	v_mfma_f32_16x16x32_bf16 v[130:133], v[8:11], v[130:133], 0
	v_add_u32_e32 v27, s26, v104
	v_add_u32_e32 v85, s26, v105
	v_add_u32_e32 v87, s26, v106
	v_mfma_f32_16x16x32_bf16 v[126:129], v[8:11], v[126:129], 0
	v_add_u32_e32 v121, s26, v107
	s_add_i32 s26, s24, 0x4000
	s_and_b32 s26, s26, 0xe000
	v_mfma_f32_16x16x32_bf16 v[8:11], v[8:11], v[122:125], 0
	ds_read_b64_tr_b16 v[142:143], v22 offset:0
	ds_read_b64_tr_b16 v[144:145], v23 offset:0
	ds_read_b64_tr_b16 v[138:139], v26 offset:0
	ds_read_b64_tr_b16 v[140:141], v27 offset:0
	ds_read_b64_tr_b16 v[122:123], v85 offset:0
	ds_read_b64_tr_b16 v[124:125], v87 offset:0
	ds_read_b64_tr_b16 v[16:17], v121 offset:0
	ds_read_b64_tr_b16 v[18:19], v146 offset:0
	s_waitcnt lgkmcnt(0)
; __device__ __forceinline__ unsigned pk2(float lo, float hi) { const f32x2_t v = {lo, hi}; return __builtin_bit_cast(unsigned, __builtin_convertvector(v, bf16x2_t)); }
; __device__ __forceinline__ f32x4 mfma16(bf16x8 a, bf16x8 b, f32x4 c) { return __builtin_amdgcn_mfma_f32_16x16x32_bf16(a, b, c, 0, 0, 0); }
; template <int KP> __device__ __forceinline__ void na_pv_step(const f32x4 (&X)[16], float inv, const unsigned (&ad)[8], int rs0, f32x4 (&O)[4]) {
;     v4u aw; aw.x = pk2(X[2 * KP][0] * inv, X[2 * KP][1] * inv); aw.y = pk2(X[2 * KP][2] * inv, X[2 * KP][3] * inv);
;     aw.z = pk2(X[2 * KP + 1][0] * inv, X[2 * KP + 1][1] * inv); aw.w = pk2(X[2 * KP + 1][2] * inv, X[2 * KP + 1][3] * inv);
;     const unsigned soff = (unsigned)((rs0 + KP) & 7) * 8192u;
;     unsigned b[8]; s16x4 vr[8];
; #pragma unroll
;     for (int x = 0; x < 8; ++x) b[x] = ad[x] + soff;
;     tr_read8<0>(b, vr);
;     const bf16x8 af = as_bf8(aw);
; #pragma unroll
;     for (int dt = 0; dt < 4; ++dt) { const bf16x8 bw = (bf16x8){vr[2 * dt][0], vr[2 * dt][1], vr[2 * dt][2], vr[2 * dt][3], vr[2 * dt + 1][0], vr[2 * dt + 1][1], vr[2 * dt + 1][2], vr[2 * dt + 1][3]};
;         O[dt] = mfma16(af, bw, O[dt]); }
; }
; __device__ __forceinline__ void na_fast(const bf16* PROJ, const float* rpb, bf16* MIX, int L, LAS unsigned char* lds) {
;     ...
;         na_pv_step<0>(X, inv, ad, rs0, O); na_pv_step<1>(X, inv, ad, rs0, O); na_pv_step<2>(X, inv, ad, rs0, O); na_pv_step<3>(X, inv, ad, rs0, O);
;         na_pv_step<4>(X, inv, ad, rs0, O); na_pv_step<5>(X, inv, ad, rs0, O); na_pv_step<6>(X, inv, ad, rs0, O); na_pv_step<7>(X, inv, ad, rs0, O);
	v_add_u32_e32 v85, s26, v105
	v_add_u32_e32 v87, s26, v106
	v_mfma_f32_16x16x32_bf16 v[134:137], v[12:15], v[142:145], v[134:137]
	v_add_u32_e32 v121, s26, v107
	s_xor_b32 s25, s25, 0x8000
	v_mfma_f32_16x16x32_bf16 v[130:133], v[12:15], v[138:141], v[130:133]
	v_add_u32_e32 v138, s26, v108
	v_mfma_f32_16x16x32_bf16 v[122:125], v[12:15], v[122:125], v[126:129]
	v_mfma_f32_16x16x32_bf16 v[8:11], v[12:15], v[16:19], v[8:11]
	v_mul_f32_e64 v12, v20, v92
	v_mul_f32_e64 v13, v21, v92
	v_pk_mul_f32 v[14:15], v[24:25], v[92:93] op_sel_hi:[1,0]
	v_cvt_pk_bf16_f32 v12, v12, v13
	v_cvt_pk_bf16_f32 v13, v14, v15
	v_pk_mul_f32 v[14:15], v[30:31], v[92:93] op_sel_hi:[1,0]
	v_pk_mul_f32 v[16:17], v[34:35], v[92:93] op_sel_hi:[1,0]
	v_cvt_pk_bf16_f32 v14, v14, v15
	v_cvt_pk_bf16_f32 v15, v16, v17
	v_add_u32_e32 v30, s26, v101
	v_add_u32_e32 v31, s26, v102
	v_add_u32_e32 v34, s26, v103
	v_add_u32_e32 v35, s26, v104
	ds_read_b64_tr_b16 v[126:127], v30 offset:0
	ds_read_b64_tr_b16 v[128:129], v31 offset:0
	ds_read_b64_tr_b16 v[24:25], v34 offset:0
	ds_read_b64_tr_b16 v[26:27], v35 offset:0
	ds_read_b64_tr_b16 v[20:21], v85 offset:0
	ds_read_b64_tr_b16 v[22:23], v87 offset:0
	ds_read_b64_tr_b16 v[16:17], v121 offset:0
	ds_read_b64_tr_b16 v[18:19], v138 offset:0
	s_waitcnt lgkmcnt(0)
	s_add_i32 s26, s24, 0x6000
	v_mfma_f32_16x16x32_bf16 v[126:129], v[12:15], v[126:129], v[134:137]
	s_and_b32 s26, s26, 0xe000
	v_add_u32_e32 v85, s26, v105
	v_add_u32_e32 v87, s26, v106
	v_mfma_f32_16x16x32_bf16 v[24:27], v[12:15], v[24:27], v[130:133]
	v_add_u32_e32 v121, s26, v107
	v_mfma_f32_16x16x32_bf16 v[20:23], v[12:15], v[20:23], v[122:125]
	s_nop 0
	v_add_u32_e32 v130, s26, v108
	v_mfma_f32_16x16x32_bf16 v[8:11], v[12:15], v[16:19], v[8:11]
	v_mul_f32_e64 v12, v28, v92
	v_mul_f32_e64 v13, v29, v92
	v_pk_mul_f32 v[14:15], v[32:33], v[92:93] op_sel_hi:[1,0]
	v_cvt_pk_bf16_f32 v12, v12, v13
	v_cvt_pk_bf16_f32 v13, v14, v15
	v_pk_mul_f32 v[14:15], v[38:39], v[92:93] op_sel_hi:[1,0]
	v_pk_mul_f32 v[16:17], v[42:43], v[92:93] op_sel_hi:[1,0]
	v_cvt_pk_bf16_f32 v14, v14, v15
	v_cvt_pk_bf16_f32 v15, v16, v17
	v_add_u32_e32 v38, s26, v101
	v_add_u32_e32 v39, s26, v102
	v_add_u32_e32 v42, s26, v103
	v_add_u32_e32 v43, s26, v104
	ds_read_b64_tr_b16 v[122:123], v38 offset:0
	ds_read_b64_tr_b16 v[124:125], v39 offset:0
	ds_read_b64_tr_b16 v[32:33], v42 offset:0
	ds_read_b64_tr_b16 v[34:35], v43 offset:0
	ds_read_b64_tr_b16 v[28:29], v85 offset:0
	ds_read_b64_tr_b16 v[30:31], v87 offset:0
	ds_read_b64_tr_b16 v[16:17], v121 offset:0
	ds_read_b64_tr_b16 v[18:19], v130 offset:0
	s_waitcnt lgkmcnt(0)
	v_add_u32_e32 v42, s25, v103
	v_mfma_f32_16x16x32_bf16 v[122:125], v[12:15], v[122:125], v[126:129]
	v_add_u32_e32 v43, s25, v104
	v_mfma_f32_16x16x32_bf16 v[24:27], v[12:15], v[32:35], v[24:27]
	v_mfma_f32_16x16x32_bf16 v[20:23], v[12:15], v[28:31], v[20:23]
	v_mfma_f32_16x16x32_bf16 v[8:11], v[12:15], v[16:19], v[8:11]
	v_mul_f32_e64 v12, v36, v92
	v_mul_f32_e64 v13, v37, v92
	v_pk_mul_f32 v[14:15], v[40:41], v[92:93] op_sel_hi:[1,0]
	v_cvt_pk_bf16_f32 v12, v12, v13
	v_cvt_pk_bf16_f32 v13, v14, v15
	v_pk_mul_f32 v[14:15], v[46:47], v[92:93] op_sel_hi:[1,0]
	v_pk_mul_f32 v[16:17], v[50:51], v[92:93] op_sel_hi:[1,0]
	v_cvt_pk_bf16_f32 v14, v14, v15
	v_cvt_pk_bf16_f32 v15, v16, v17
	v_add_u32_e32 v40, s25, v101
	v_add_u32_e32 v41, s25, v102
	v_add_u32_e32 v46, s25, v105
	v_add_u32_e32 v47, s25, v106
	v_add_u32_e32 v50, s25, v107
	v_add_u32_e32 v51, s25, v108
	ds_read_b64_tr_b16 v[36:37], v40 offset:0
	ds_read_b64_tr_b16 v[38:39], v41 offset:0
	ds_read_b64_tr_b16 v[32:33], v42 offset:0
	ds_read_b64_tr_b16 v[34:35], v43 offset:0
	ds_read_b64_tr_b16 v[28:29], v46 offset:0
	ds_read_b64_tr_b16 v[30:31], v47 offset:0
	ds_read_b64_tr_b16 v[16:17], v50 offset:0
	ds_read_b64_tr_b16 v[18:19], v51 offset:0
	s_waitcnt lgkmcnt(0)
	s_add_i32 s25, s24, 0xa000
	v_mfma_f32_16x16x32_bf16 v[36:39], v[12:15], v[36:39], v[122:125]
	s_and_b32 s25, s25, 0xe000
	v_add_u32_e32 v46, s25, v103
	v_add_u32_e32 v47, s25, v104
	v_mfma_f32_16x16x32_bf16 v[24:27], v[12:15], v[32:35], v[24:27]
	v_add_u32_e32 v50, s25, v107
	v_add_u32_e32 v51, s25, v108
	v_mfma_f32_16x16x32_bf16 v[20:23], v[12:15], v[28:31], v[20:23]
	v_mfma_f32_16x16x32_bf16 v[8:11], v[12:15], v[16:19], v[8:11]
	v_mul_f32_e64 v12, v44, v92
	v_mul_f32_e64 v13, v45, v92
	v_pk_mul_f32 v[14:15], v[48:49], v[92:93] op_sel_hi:[1,0]
	v_cvt_pk_bf16_f32 v12, v12, v13
	v_cvt_pk_bf16_f32 v13, v14, v15
	v_pk_mul_f32 v[14:15], v[54:55], v[92:93] op_sel_hi:[1,0]
	v_pk_mul_f32 v[16:17], v[58:59], v[92:93] op_sel_hi:[1,0]
	v_cvt_pk_bf16_f32 v14, v14, v15
	v_cvt_pk_bf16_f32 v15, v16, v17
	v_add_u32_e32 v44, s25, v101
	v_add_u32_e32 v45, s25, v102
	v_add_u32_e32 v48, s25, v105
	v_add_u32_e32 v49, s25, v106
	ds_read_b64_tr_b16 v[40:41], v44 offset:0
	ds_read_b64_tr_b16 v[42:43], v45 offset:0
	ds_read_b64_tr_b16 v[32:33], v46 offset:0
	ds_read_b64_tr_b16 v[34:35], v47 offset:0
	ds_read_b64_tr_b16 v[28:29], v48 offset:0
	ds_read_b64_tr_b16 v[30:31], v49 offset:0
	ds_read_b64_tr_b16 v[16:17], v50 offset:0
	ds_read_b64_tr_b16 v[18:19], v51 offset:0
	s_waitcnt lgkmcnt(0)
; #define LAS __attribute__((address_space(3)))
; __device__ __forceinline__ unsigned f2bf(float f) { return pk2(f, 0.f) & 0xffffu; }
; __device__ __forceinline__ void na_fast(const bf16* PROJ, const float* rpb, bf16* MIX, int L, LAS unsigned char* lds) {
;     ...
;         na_pv_step<4>(X, inv, ad, rs0, O); na_pv_step<5>(X, inv, ad, rs0, O); na_pv_step<6>(X, inv, ad, rs0, O); na_pv_step<7>(X, inv, ad, rs0, O);
; #pragma unroll
;         for (int dt = 0; dt < 4; ++dt)
; #pragma unroll
;             for (int rr = 0; rr < 4; ++rr) MIX[(seqbase + (size_t)r * 64 + 16 * j + 4 * g4 + rr) * D + 512 + 64 * h + 16 * dt + r16] = (bf16)f2bf(O[dt][rr]);
;         if (more) {
;             __syncthreads();
; #pragma unroll
;             for (int m = 0; m < 2; ++m) { const int cid = tid + 512 * m, c = cid & 7, h2 = (cid >> 3) & 1, col = cid >> 4, slot = (rs0n + 7) & 7;
;                 *(LAS v4u*)(VI + h2 * 65536 + (slot * 64 + col) * 128 + ((c ^ (((col >> 1) & 3) * 2)) * 16)) = nw[m]; } }
	s_add_i32 s25, s24, 0xc000
	v_mfma_f32_16x16x32_bf16 v[36:39], v[12:15], v[40:43], v[36:39]
	s_and_b32 s25, s25, 0xe000
	v_add_u32_e32 v44, s25, v101
	v_add_u32_e32 v45, s25, v102
	v_mfma_f32_16x16x32_bf16 v[24:27], v[12:15], v[32:35], v[24:27]
	v_add_u32_e32 v46, s25, v103
	v_add_u32_e32 v47, s25, v104
	v_add_u32_e32 v48, s25, v105
	v_mfma_f32_16x16x32_bf16 v[20:23], v[12:15], v[28:31], v[20:23]
	v_add_u32_e32 v49, s25, v106
	v_add_u32_e32 v50, s25, v107
	v_add_u32_e32 v51, s25, v108
	v_mfma_f32_16x16x32_bf16 v[8:11], v[12:15], v[16:19], v[8:11]
	v_mul_f32_e64 v12, v52, v92
	v_mul_f32_e64 v13, v53, v92
	v_pk_mul_f32 v[14:15], v[56:57], v[92:93] op_sel_hi:[1,0]
	v_cvt_pk_bf16_f32 v12, v12, v13
	v_cvt_pk_bf16_f32 v13, v14, v15
	v_pk_mul_f32 v[14:15], v[62:63], v[92:93] op_sel_hi:[1,0]
	v_pk_mul_f32 v[16:17], v[68:69], v[92:93] op_sel_hi:[1,0]
	v_cvt_pk_bf16_f32 v14, v14, v15
	v_cvt_pk_bf16_f32 v15, v16, v17
	ds_read_b64_tr_b16 v[40:41], v44 offset:0
	ds_read_b64_tr_b16 v[42:43], v45 offset:0
	ds_read_b64_tr_b16 v[32:33], v46 offset:0
	ds_read_b64_tr_b16 v[34:35], v47 offset:0
	ds_read_b64_tr_b16 v[28:29], v48 offset:0
	ds_read_b64_tr_b16 v[30:31], v49 offset:0
	ds_read_b64_tr_b16 v[16:17], v50 offset:0
	ds_read_b64_tr_b16 v[18:19], v51 offset:0
	s_waitcnt lgkmcnt(0)
	s_add_i32 s24, s24, 0xe000
	s_and_b32 s24, s24, 0xe000
	v_mfma_f32_16x16x32_bf16 v[36:39], v[12:15], v[40:43], v[36:39]
	v_add_u32_e32 v44, s24, v101
	v_add_u32_e32 v45, s24, v102
	v_add_u32_e32 v46, s24, v103
	v_mfma_f32_16x16x32_bf16 v[24:27], v[12:15], v[32:35], v[24:27]
	v_add_u32_e32 v47, s24, v104
	v_add_u32_e32 v48, s24, v105
	v_add_u32_e32 v49, s24, v106
	v_mfma_f32_16x16x32_bf16 v[20:23], v[12:15], v[28:31], v[20:23]
	v_add_u32_e32 v50, s24, v107
	v_add_u32_e32 v51, s24, v108
	s_mov_b32 s24, 0x6d00000
	v_mfma_f32_16x16x32_bf16 v[8:11], v[12:15], v[16:19], v[8:11]
	v_mul_f32_e64 v12, v60, v92
	v_mul_f32_e64 v13, v61, v92
	v_pk_mul_f32 v[14:15], v[66:67], v[92:93] op_sel_hi:[1,0]
	v_cvt_pk_bf16_f32 v12, v12, v13
	v_cvt_pk_bf16_f32 v13, v14, v15
	v_pk_mul_f32 v[14:15], v[70:71], v[92:93] op_sel_hi:[1,0]
	v_pk_mul_f32 v[16:17], v[72:73], v[92:93] op_sel_hi:[1,0]
	v_cvt_pk_bf16_f32 v14, v14, v15
	v_cvt_pk_bf16_f32 v15, v16, v17
	ds_read_b64_tr_b16 v[40:41], v44 offset:0
	ds_read_b64_tr_b16 v[42:43], v45 offset:0
	ds_read_b64_tr_b16 v[32:33], v46 offset:0
	ds_read_b64_tr_b16 v[34:35], v47 offset:0
	ds_read_b64_tr_b16 v[28:29], v48 offset:0
	ds_read_b64_tr_b16 v[30:31], v49 offset:0
	ds_read_b64_tr_b16 v[16:17], v50 offset:0
	ds_read_b64_tr_b16 v[18:19], v51 offset:0
	s_waitcnt lgkmcnt(0)
	s_nop 1
	v_mfma_f32_16x16x32_bf16 v[36:39], v[12:15], v[40:43], v[36:39]
	v_mfma_f32_16x16x32_bf16 v[24:27], v[12:15], v[32:35], v[24:27]
	v_mfma_f32_16x16x32_bf16 v[20:23], v[12:15], v[28:31], v[20:23]
	v_mfma_f32_16x16x32_bf16 v[8:11], v[12:15], v[16:19], v[8:11]
	v_lshl_add_u64 v[12:13], v[90:91], 0, s[6:7]
	v_add_co_u32_e32 v14, vcc, s24, v12
	s_nop 2
	v_cvt_pk_bf16_f32 v16, v36, s0
	v_addc_co_u32_e32 v15, vcc, 0, v13, vcc
	s_mov_b32 s24, 0x6d01000
	global_store_short v[14:15], v16, off offset:1024
	v_cvt_pk_bf16_f32 v16, v37, s0
	v_add_co_u32_e32 v12, vcc, s24, v12
	global_store_short v[14:15], v16, off offset:3072
	v_cvt_pk_bf16_f32 v16, v38, s0
	v_addc_co_u32_e32 v13, vcc, 0, v13, vcc
	global_store_short v[12:13], v16, off offset:1024
	v_cvt_pk_bf16_f32 v16, v39, s0
	global_store_short v[12:13], v16, off offset:3072
	v_cvt_pk_bf16_f32 v16, v24, s0
	global_store_short v[14:15], v16, off offset:1056
	v_cvt_pk_bf16_f32 v16, v25, s0
	global_store_short v[14:15], v16, off offset:3104
	v_cvt_pk_bf16_f32 v16, v26, s0
	global_store_short v[12:13], v16, off offset:1056
	v_cvt_pk_bf16_f32 v16, v27, s0
	global_store_short v[12:13], v16, off offset:3104
	v_cvt_pk_bf16_f32 v16, v20, s0
	v_cvt_pk_bf16_f32 v8, v8, s0
	global_store_short v[14:15], v16, off offset:1088
	v_cvt_pk_bf16_f32 v16, v21, s0
	global_store_short v[14:15], v8, off offset:1120
	v_cvt_pk_bf16_f32 v8, v9, s0
	global_store_short v[14:15], v16, off offset:3136
	v_cvt_pk_bf16_f32 v16, v22, s0
	global_store_short v[14:15], v8, off offset:3168
	v_cvt_pk_bf16_f32 v8, v10, s0
	global_store_short v[12:13], v16, off offset:1088
	v_cvt_pk_bf16_f32 v16, v23, s0
	global_store_short v[12:13], v8, off offset:1120
	v_cvt_pk_bf16_f32 v8, v11, s0
	s_and_b64 vcc, exec, s[64:65]
	global_store_short v[12:13], v16, off offset:3136
	global_store_short v[12:13], v8, off offset:3168
	s_cbranch_vccnz .LBB0_450
	s_lshl_b32 s1, s1, 6
	s_addk_i32 s1, 0x1c0
	s_and_b32 s1, s1, 0x1c0
	v_add_u32_e32 v8, s1, v115
	v_lshl_add_u32 v8, v8, 7, v110
	s_barrier
	ds_write_b128 v8, v[0:3]
	v_add_u32_e32 v8, s1, v116
	v_lshl_add_u32 v8, v8, 7, v110
	ds_write_b128 v8, v[4:7]
	s_branch .LBB0_450
